# MLA: tile loads later still (waves 0-3 behind their 1st QK MFMA, waves 4-7 behind their 4th PV MFMA)
# baseline (speedup 1.0000x reference)
; __device__ __forceinline__ void finishSM9(f32x16& p0, f32x16& p1, float alpha, float& l_reg, v8i32& p8) {
; #pragma unroll
;   for (int r = 0; r < 16; ++r) { p0[r] = __builtin_amdgcn_exp2f(p0[r]); p1[r] = __builtin_amdgcn_exp2f(p1[r]); }
;   float ps = 0;
; #pragma unroll
;   for (int r = 0; r < 16; ++r) ps += p0[r];
; #pragma unroll
;   for (int r = 0; r < 16; ++r) ps += p1[r];
;   { auto rr = __builtin_amdgcn_permlane32_swap(__float_as_uint(ps), __float_as_uint(ps), false, false);
;     ps = __uint_as_float(rr[0]) + __uint_as_float(rr[1]); }
;   l_reg = l_reg * alpha + ps;
; #pragma unroll
;   for (int g = 0; g < 4; ++g) {
;     int w = __builtin_amdgcn_cvt_pk_fp8_f32(p0[4 * g], p0[4 * g + 1], 0, false); p8[g] = __builtin_amdgcn_cvt_pk_fp8_f32(p0[4 * g + 2], p0[4 * g + 3], w, true);
;     int u = __builtin_amdgcn_cvt_pk_fp8_f32(p1[4 * g], p1[4 * g + 1], 0, false); p8[4 + g] = __builtin_amdgcn_cvt_pk_fp8_f32(p1[4 * g + 2], p1[4 * g + 3], u, true); }
; }
; __device__ __forceinline__ void pv8(f32x16* o, const char* Vt, const v8i32 p8, int r32, int hi) {
;   const int sw = (r32 >> 2) & 3, a0 = r32 * 64 + (((hi * 2) ^ sw) << 4), a1 = r32 * 64 + (((hi * 2 + 1) ^ sw) << 4);
; #pragma unroll
;   for (int d0 = 0; d0 < 4; ++d0) {
;     const v8i32 vf = cat8(*reinterpret_cast<const v4i32*>(Vt + d0 * 2048 + a0), *reinterpret_cast<const v4i32*>(Vt + d0 * 2048 + a1));
;     o[d0] = __builtin_amdgcn_mfma_scale_f32_32x32x64_f8f6f4(p8, vf, o[d0], 0, 0, 0, 127, 0, 127); }
; }
; __device__ __forceinline__ void qkt9(f32x16& p0, f32x16& p1, const char* Kn, const char* Kr, const v8i32* qf, const float init, int r32, int hi) {
; #pragma unroll
;   for (int r = 0; r < 16; ++r) { p0[r] = init; p1[r] = init; }
; #pragma unroll
;   for (int s = 0; s < 2; ++s) { const int c0 = s * 4 + hi * 2;
;     const v8i32 a0 = cat8(*reinterpret_cast<const v4i32*>(Kn + KN8SW(r32, c0)), *reinterpret_cast<const v4i32*>(Kn + KN8SW(r32, c0 + 1)));
;     const v8i32 a1 = cat8(*reinterpret_cast<const v4i32*>(Kn + 4096 + KN8SW(r32, c0)), *reinterpret_cast<const v4i32*>(Kn + 4096 + KN8SW(r32, c0 + 1)));
;     p0 = __builtin_amdgcn_mfma_scale_f32_32x32x64_f8f6f4(a0, qf[s], p0, 0, 0, 0, 127, 0, 124);
;     p1 = __builtin_amdgcn_mfma_scale_f32_32x32x64_f8f6f4(a1, qf[s], p1, 0, 0, 0, 127, 0, 124); }
;   { const int c0 = hi * 2;
.LBB0_1321:
	ds_read_b128 v[114:117], v215 offset:24576
	ds_read_b128 v[118:121], v216 offset:24576
	ds_read_b128 v[222:225], v215 offset:28672
	ds_read_b128 v[226:229], v216 offset:28672
	v_exp_f32_e32 v0, v82
	v_exp_f32_e32 v177, v83
	v_exp_f32_e32 v179, v84
	v_exp_f32_e32 v254, v85
	v_add_f32_e32 v219, v0, v177
	v_cvt_pk_fp8_f32 v246, v0, v177
	v_add_f32_e32 v219, v179, v219
	v_add_f32_e32 v219, v254, v219
	v_cvt_pk_fp8_f32 v246, v179, v254 op_sel:[0,0,1]
	s_waitcnt lgkmcnt(2)
	v_mfma_scale_f32_32x32x64_f8f6f4 v[114:129], v[114:121], v[146:153], v[230:245], v194, v193 op_sel_hi:[0,0,0]
	global_load_dwordx4 v[158:161], v176, s[18:19]
	global_load_dwordx4 v[162:165], v178, s[16:17]
	global_load_dwordx4 v[154:157], v[180:181], off
	v_add_u32_e32 v176, 0x2000, v176
	v_add_u32_e32 v178, 0x20000, v178
	s_mov_b64 s[20:21], 0x1000
	v_lshl_add_u64 v[180:181], v[180:181], 0, s[20:21]
	v_exp_f32_e32 v0, v86
	v_exp_f32_e32 v177, v87
	v_exp_f32_e32 v179, v88
	v_exp_f32_e32 v254, v89
	v_add_f32_e32 v219, v0, v219
	v_add_f32_e32 v219, v177, v219
	v_cvt_pk_fp8_f32 v247, v0, v177
	v_add_f32_e32 v219, v179, v219
	v_add_f32_e32 v219, v254, v219
	v_cvt_pk_fp8_f32 v247, v179, v254 op_sel:[0,0,1]
	ds_read_b128 v[82:85], v213 offset:24576
	ds_read_b128 v[86:89], v214 offset:24576
	s_waitcnt lgkmcnt(2)
	v_mfma_scale_f32_32x32x64_f8f6f4 v[98:113], v[222:229], v[146:153], v[230:245], v194, v193 op_sel_hi:[0,0,0]
	ds_read_b128 v[222:225], v213 offset:28672
	ds_read_b128 v[226:229], v214 offset:28672
	v_exp_f32_e32 v0, v90
	v_exp_f32_e32 v177, v91
	v_exp_f32_e32 v179, v92
	v_exp_f32_e32 v254, v93
	v_add_f32_e32 v219, v0, v219
	v_add_f32_e32 v219, v177, v219
	v_cvt_pk_fp8_f32 v248, v0, v177
	v_add_f32_e32 v219, v179, v219
	v_add_f32_e32 v219, v254, v219
	v_cvt_pk_fp8_f32 v248, v179, v254 op_sel:[0,0,1]
	v_exp_f32_e32 v0, v94
	v_exp_f32_e32 v177, v95
	v_exp_f32_e32 v179, v96
	v_exp_f32_e32 v254, v97
	v_add_f32_e32 v219, v0, v219
	v_add_f32_e32 v219, v177, v219
	v_cvt_pk_fp8_f32 v249, v0, v177
	v_add_f32_e32 v219, v179, v219
	v_add_f32_e32 v219, v254, v219
	v_cvt_pk_fp8_f32 v249, v179, v254 op_sel:[0,0,1]
	ds_read_b128 v[90:93], v185 offset:36864
	ds_read_b128 v[94:97], v186 offset:36864
	s_waitcnt lgkmcnt(4)
	v_mfma_scale_f32_32x32x64_f8f6f4 v[114:129], v[82:89], v[138:145], v[114:129], v194, v193 op_sel_hi:[0,0,0]
	v_exp_f32_e32 v0, v66
	v_exp_f32_e32 v177, v67
	v_exp_f32_e32 v179, v68
	v_exp_f32_e32 v254, v69
	v_add_f32_e32 v219, v0, v219
	v_add_f32_e32 v219, v177, v219
	v_cvt_pk_fp8_f32 v250, v0, v177
	v_add_f32_e32 v219, v179, v219
	v_add_f32_e32 v219, v254, v219
	v_cvt_pk_fp8_f32 v250, v179, v254 op_sel:[0,0,1]
	s_waitcnt lgkmcnt(2)
	v_mfma_scale_f32_32x32x64_f8f6f4 v[98:113], v[222:229], v[138:145], v[98:113], v194, v193 op_sel_hi:[0,0,0]
	ds_read_b128 v[222:225], v185 offset:38912
	ds_read_b128 v[226:229], v186 offset:38912
	v_exp_f32_e32 v0, v70
	v_exp_f32_e32 v177, v71
	v_exp_f32_e32 v179, v72
	v_exp_f32_e32 v254, v73
	v_add_f32_e32 v219, v0, v219
	v_add_f32_e32 v219, v177, v219
	v_cvt_pk_fp8_f32 v251, v0, v177
	v_add_f32_e32 v219, v179, v219
	v_add_f32_e32 v219, v254, v219
	v_cvt_pk_fp8_f32 v251, v179, v254 op_sel:[0,0,1]
	v_exp_f32_e32 v0, v74
	v_exp_f32_e32 v177, v75
	v_exp_f32_e32 v179, v76
	v_exp_f32_e32 v254, v77
	v_add_f32_e32 v219, v0, v219
	v_add_f32_e32 v219, v177, v219
	v_cvt_pk_fp8_f32 v252, v0, v177
	v_add_f32_e32 v219, v179, v219
	v_add_f32_e32 v219, v254, v219
	v_cvt_pk_fp8_f32 v252, v179, v254 op_sel:[0,0,1]
	s_waitcnt lgkmcnt(2)
	v_mfma_scale_f32_32x32x64_f8f6f4 v[114:129], v[90:97], v[130:137], v[114:129], v194, v193 op_sel_hi:[0,0,0]
	v_exp_f32_e32 v0, v78
	v_exp_f32_e32 v177, v79
	v_exp_f32_e32 v179, v80
	v_exp_f32_e32 v254, v81
	v_add_f32_e32 v219, v0, v219
	v_add_f32_e32 v219, v177, v219
	v_cvt_pk_fp8_f32 v253, v0, v177
	v_add_f32_e32 v219, v179, v219
	v_add_f32_e32 v219, v254, v219
	v_cvt_pk_fp8_f32 v253, v179, v254 op_sel:[0,0,1]
	ds_read_b128 v[90:93], v185 offset:0
	ds_read_b128 v[94:97], v186 offset:0
	ds_read_b128 v[82:85], v185 offset:2048
	ds_read_b128 v[86:89], v186 offset:2048
	ds_read_b128 v[74:77], v185 offset:4096
	ds_read_b128 v[78:81], v186 offset:4096
	ds_read_b128 v[66:69], v185 offset:6144
	ds_read_b128 v[70:73], v186 offset:6144
	s_waitcnt lgkmcnt(8)
	v_mfma_scale_f32_32x32x64_f8f6f4 v[98:113], v[222:229], v[130:137], v[98:113], v194, v193 op_sel_hi:[0,0,0]
	v_mov_b32_e32 v0, v219
	s_nop 1
	v_permlane32_swap_b32_e32 v219, v0
	v_add_f32_e32 v219, v219, v0
	v_fma_f32 v209, v209, v218, v219
	v_max_f32_e32 v177, v114, v115
	v_max3_f32 v177, v177, v116, v117
	v_max3_f32 v177, v177, v118, v119
	v_max3_f32 v177, v177, v120, v121
	v_max3_f32 v177, v177, v122, v123
	v_max3_f32 v177, v177, v124, v125
	v_max3_f32 v177, v177, v126, v127
	v_max3_f32 v177, v177, v128, v129
	s_waitcnt lgkmcnt(6)
	v_mfma_scale_f32_32x32x64_f8f6f4 v[50:65], v[246:253], v[90:97], v[50:65], v194, v194 op_sel_hi:[0,0,0]
	s_waitcnt lgkmcnt(4)
	v_mfma_scale_f32_32x32x64_f8f6f4 v[34:49], v[246:253], v[82:89], v[34:49], v194, v194 op_sel_hi:[0,0,0]
	s_waitcnt lgkmcnt(2)
	v_mfma_scale_f32_32x32x64_f8f6f4 v[18:33], v[246:253], v[74:81], v[18:33], v194, v194 op_sel_hi:[0,0,0]
	s_waitcnt vmcnt(0)
	ds_write_b128 v210, v[158:161] offset:43008
	ds_write_b128 v211, v[162:165] offset:51200
	ds_write_b128 v212, v[154:157] offset:59392
	s_waitcnt lgkmcnt(3)
	v_mfma_scale_f32_32x32x64_f8f6f4 v[2:17], v[246:253], v[66:73], v[2:17], v194, v194 op_sel_hi:[0,0,0]
	s_waitcnt lgkmcnt(0)
	s_barrier
	v_max_f32_e32 v0, v98, v99
	v_max3_f32 v0, v0, v100, v101
	v_max3_f32 v0, v0, v102, v103
	v_max3_f32 v0, v0, v104, v105
	v_max3_f32 v0, v0, v106, v107
	v_max3_f32 v0, v0, v108, v109
	v_max3_f32 v0, v0, v110, v111
	v_max3_f32 v0, v0, v112, v113
	v_max_f32_e32 v177, v177, v0
	v_mov_b32_e32 v0, v177
	v_mov_b32_e32 v221, 1.0
	s_nop 0
	v_permlane32_swap_b32_e32 v177, v0
	v_max_f32_e32 v177, v177, v0
	v_cmp_ge_f32_e32 vcc, s90, v177
	s_cmp_eq_u64 vcc, exec
	s_cbranch_scc0 .Lmla_h0_newmax
; __device__ __forceinline__ void finishSM9(f32x16& p0, f32x16& p1, float alpha, float& l_reg, v8i32& p8) {
; #pragma unroll
;   for (int r = 0; r < 16; ++r) { p0[r] = __builtin_amdgcn_exp2f(p0[r]); p1[r] = __builtin_amdgcn_exp2f(p1[r]); }
;   float ps = 0;
; #pragma unroll
;   for (int r = 0; r < 16; ++r) ps += p0[r];
; #pragma unroll
;   for (int r = 0; r < 16; ++r) ps += p1[r];
;   { auto rr = __builtin_amdgcn_permlane32_swap(__float_as_uint(ps), __float_as_uint(ps), false, false);
;     ps = __uint_as_float(rr[0]) + __uint_as_float(rr[1]); }
;   l_reg = l_reg * alpha + ps;
; #pragma unroll
;   for (int g = 0; g < 4; ++g) {
;     int w = __builtin_amdgcn_cvt_pk_fp8_f32(p0[4 * g], p0[4 * g + 1], 0, false); p8[g] = __builtin_amdgcn_cvt_pk_fp8_f32(p0[4 * g + 2], p0[4 * g + 3], w, true);
;     int u = __builtin_amdgcn_cvt_pk_fp8_f32(p1[4 * g], p1[4 * g + 1], 0, false); p8[4 + g] = __builtin_amdgcn_cvt_pk_fp8_f32(p1[4 * g + 2], p1[4 * g + 3], u, true); }
; }
; __device__ __forceinline__ void pv8(f32x16* o, const char* Vt, const v8i32 p8, int r32, int hi) {
;   const int sw = (r32 >> 2) & 3, a0 = r32 * 64 + (((hi * 2) ^ sw) << 4), a1 = r32 * 64 + (((hi * 2 + 1) ^ sw) << 4);
; #pragma unroll
;   for (int d0 = 0; d0 < 4; ++d0) {
;     const v8i32 vf = cat8(*reinterpret_cast<const v4i32*>(Vt + d0 * 2048 + a0), *reinterpret_cast<const v4i32*>(Vt + d0 * 2048 + a1));
;     o[d0] = __builtin_amdgcn_mfma_scale_f32_32x32x64_f8f6f4(p8, vf, o[d0], 0, 0, 0, 127, 0, 127); }
; }
; __device__ __forceinline__ void qkt9(f32x16& p0, f32x16& p1, const char* Kn, const char* Kr, const v8i32* qf, const float init, int r32, int hi) {
; #pragma unroll
;   for (int r = 0; r < 16; ++r) { p0[r] = init; p1[r] = init; }
; #pragma unroll
;   for (int s = 0; s < 2; ++s) { const int c0 = s * 4 + hi * 2;
;     const v8i32 a0 = cat8(*reinterpret_cast<const v4i32*>(Kn + KN8SW(r32, c0)), *reinterpret_cast<const v4i32*>(Kn + KN8SW(r32, c0 + 1)));
;     const v8i32 a1 = cat8(*reinterpret_cast<const v4i32*>(Kn + 4096 + KN8SW(r32, c0)), *reinterpret_cast<const v4i32*>(Kn + 4096 + KN8SW(r32, c0 + 1)));
;     p0 = __builtin_amdgcn_mfma_scale_f32_32x32x64_f8f6f4(a0, qf[s], p0, 0, 0, 0, 127, 0, 124);
;     p1 = __builtin_amdgcn_mfma_scale_f32_32x32x64_f8f6f4(a1, qf[s], p1, 0, 0, 0, 127, 0, 124); }
;   { const int c0 = hi * 2;
.Lmla_h0_cont:
	ds_read_b128 v[82:85], v215 offset:51200
	ds_read_b128 v[86:89], v216 offset:51200
	ds_read_b128 v[222:225], v215 offset:55296
	ds_read_b128 v[226:229], v216 offset:55296
	v_exp_f32_e32 v0, v114
	v_exp_f32_e32 v177, v115
	v_exp_f32_e32 v179, v116
	v_exp_f32_e32 v254, v117
	v_add_f32_e32 v219, v0, v177
	v_cvt_pk_fp8_f32 v246, v0, v177
	v_add_f32_e32 v219, v179, v219
	v_add_f32_e32 v219, v254, v219
	v_cvt_pk_fp8_f32 v246, v179, v254 op_sel:[0,0,1]
	s_waitcnt lgkmcnt(2)
	v_mfma_scale_f32_32x32x64_f8f6f4 v[82:97], v[82:89], v[146:153], v[230:245], v194, v193 op_sel_hi:[0,0,0]
	global_load_dwordx4 v[158:161], v176, s[18:19]
	global_load_dwordx4 v[162:165], v178, s[16:17]
	global_load_dwordx4 v[154:157], v[180:181], off
	v_add_u32_e32 v176, 0x2000, v176
	v_add_u32_e32 v178, 0x20000, v178
	s_mov_b64 s[20:21], 0x1000
	v_lshl_add_u64 v[180:181], v[180:181], 0, s[20:21]
	v_exp_f32_e32 v0, v118
	v_exp_f32_e32 v177, v119
	v_exp_f32_e32 v179, v120
	v_exp_f32_e32 v254, v121
	v_add_f32_e32 v219, v0, v219
	v_add_f32_e32 v219, v177, v219
	v_cvt_pk_fp8_f32 v247, v0, v177
	v_add_f32_e32 v219, v179, v219
	v_add_f32_e32 v219, v254, v219
	v_cvt_pk_fp8_f32 v247, v179, v254 op_sel:[0,0,1]
	ds_read_b128 v[114:117], v213 offset:51200
	ds_read_b128 v[118:121], v214 offset:51200
	s_waitcnt lgkmcnt(2)
	v_mfma_scale_f32_32x32x64_f8f6f4 v[66:81], v[222:229], v[146:153], v[230:245], v194, v193 op_sel_hi:[0,0,0]
	ds_read_b128 v[222:225], v213 offset:55296
	ds_read_b128 v[226:229], v214 offset:55296
	v_exp_f32_e32 v0, v122
	v_exp_f32_e32 v177, v123
	v_exp_f32_e32 v179, v124
	v_exp_f32_e32 v254, v125
	v_add_f32_e32 v219, v0, v219
	v_add_f32_e32 v219, v177, v219
	v_cvt_pk_fp8_f32 v248, v0, v177
	v_add_f32_e32 v219, v179, v219
	v_add_f32_e32 v219, v254, v219
	v_cvt_pk_fp8_f32 v248, v179, v254 op_sel:[0,0,1]
	v_exp_f32_e32 v0, v126
	v_exp_f32_e32 v177, v127
	v_exp_f32_e32 v179, v128
	v_exp_f32_e32 v254, v129
	v_add_f32_e32 v219, v0, v219
	v_add_f32_e32 v219, v177, v219
	v_cvt_pk_fp8_f32 v249, v0, v177
	v_add_f32_e32 v219, v179, v219
	v_add_f32_e32 v219, v254, v219
	v_cvt_pk_fp8_f32 v249, v179, v254 op_sel:[0,0,1]
	ds_read_b128 v[122:125], v185 offset:59392
	ds_read_b128 v[126:129], v186 offset:59392
	s_waitcnt lgkmcnt(4)
	v_mfma_scale_f32_32x32x64_f8f6f4 v[82:97], v[114:121], v[138:145], v[82:97], v194, v193 op_sel_hi:[0,0,0]
	v_exp_f32_e32 v0, v98
	v_exp_f32_e32 v177, v99
	v_exp_f32_e32 v179, v100
	v_exp_f32_e32 v254, v101
	v_add_f32_e32 v219, v0, v219
	v_add_f32_e32 v219, v177, v219
	v_cvt_pk_fp8_f32 v250, v0, v177
	v_add_f32_e32 v219, v179, v219
	v_add_f32_e32 v219, v254, v219
	v_cvt_pk_fp8_f32 v250, v179, v254 op_sel:[0,0,1]
	s_waitcnt lgkmcnt(2)
	v_mfma_scale_f32_32x32x64_f8f6f4 v[66:81], v[222:229], v[138:145], v[66:81], v194, v193 op_sel_hi:[0,0,0]
	ds_read_b128 v[222:225], v185 offset:61440
	ds_read_b128 v[226:229], v186 offset:61440
	v_exp_f32_e32 v0, v102
	v_exp_f32_e32 v177, v103
	v_exp_f32_e32 v179, v104
	v_exp_f32_e32 v254, v105
	v_add_f32_e32 v219, v0, v219
	v_add_f32_e32 v219, v177, v219
	v_cvt_pk_fp8_f32 v251, v0, v177
	v_add_f32_e32 v219, v179, v219
	v_add_f32_e32 v219, v254, v219
	v_cvt_pk_fp8_f32 v251, v179, v254 op_sel:[0,0,1]
	v_exp_f32_e32 v0, v106
	v_exp_f32_e32 v177, v107
	v_exp_f32_e32 v179, v108
	v_exp_f32_e32 v254, v109
	v_add_f32_e32 v219, v0, v219
	v_add_f32_e32 v219, v177, v219
	v_cvt_pk_fp8_f32 v252, v0, v177
	v_add_f32_e32 v219, v179, v219
	v_add_f32_e32 v219, v254, v219
	v_cvt_pk_fp8_f32 v252, v179, v254 op_sel:[0,0,1]
	s_waitcnt lgkmcnt(2)
	v_mfma_scale_f32_32x32x64_f8f6f4 v[82:97], v[122:129], v[130:137], v[82:97], v194, v193 op_sel_hi:[0,0,0]
	v_exp_f32_e32 v0, v110
	v_exp_f32_e32 v177, v111
	v_exp_f32_e32 v179, v112
	v_exp_f32_e32 v254, v113
	v_add_f32_e32 v219, v0, v219
	v_add_f32_e32 v219, v177, v219
	v_cvt_pk_fp8_f32 v253, v0, v177
	v_add_f32_e32 v219, v179, v219
	v_add_f32_e32 v219, v254, v219
	v_cvt_pk_fp8_f32 v253, v179, v254 op_sel:[0,0,1]
	ds_read_b128 v[122:125], v185 offset:8192
	ds_read_b128 v[126:129], v186 offset:8192
	ds_read_b128 v[114:117], v185 offset:10240
	ds_read_b128 v[118:121], v186 offset:10240
	ds_read_b128 v[106:109], v185 offset:12288
	ds_read_b128 v[110:113], v186 offset:12288
	ds_read_b128 v[98:101], v185 offset:14336
	ds_read_b128 v[102:105], v186 offset:14336
	s_waitcnt lgkmcnt(8)
	v_mfma_scale_f32_32x32x64_f8f6f4 v[66:81], v[222:229], v[130:137], v[66:81], v194, v193 op_sel_hi:[0,0,0]
	v_mov_b32_e32 v0, v219
	s_nop 1
	v_permlane32_swap_b32_e32 v219, v0
	v_add_f32_e32 v219, v219, v0
	v_fma_f32 v209, v209, v221, v219
	v_max_f32_e32 v177, v82, v83
	v_max3_f32 v177, v177, v84, v85
	v_max3_f32 v177, v177, v86, v87
	v_max3_f32 v177, v177, v88, v89
	v_max3_f32 v177, v177, v90, v91
	v_max3_f32 v177, v177, v92, v93
	v_max3_f32 v177, v177, v94, v95
	v_max3_f32 v177, v177, v96, v97
	s_waitcnt lgkmcnt(6)
	v_mfma_scale_f32_32x32x64_f8f6f4 v[50:65], v[246:253], v[122:129], v[50:65], v194, v194 op_sel_hi:[0,0,0]
	s_waitcnt lgkmcnt(4)
	v_mfma_scale_f32_32x32x64_f8f6f4 v[34:49], v[246:253], v[114:121], v[34:49], v194, v194 op_sel_hi:[0,0,0]
	s_waitcnt lgkmcnt(2)
	v_mfma_scale_f32_32x32x64_f8f6f4 v[18:33], v[246:253], v[106:113], v[18:33], v194, v194 op_sel_hi:[0,0,0]
	s_waitcnt vmcnt(0)
	ds_write_b128 v210, v[158:161]
	ds_write_b128 v211, v[162:165] offset:16384
	ds_write_b128 v212, v[154:157] offset:32768
	s_waitcnt lgkmcnt(3)
	v_mfma_scale_f32_32x32x64_f8f6f4 v[2:17], v[246:253], v[98:105], v[2:17], v194, v194 op_sel_hi:[0,0,0]
	s_waitcnt lgkmcnt(0)
	s_barrier
	v_max_f32_e32 v0, v66, v67
	v_max3_f32 v0, v0, v68, v69
	v_max3_f32 v0, v0, v70, v71
	v_max3_f32 v0, v0, v72, v73
	v_max3_f32 v0, v0, v74, v75
	v_max3_f32 v0, v0, v76, v77
	v_max3_f32 v0, v0, v78, v79
	v_max3_f32 v0, v0, v80, v81
	v_max_f32_e32 v177, v177, v0
	v_mov_b32_e32 v0, v177
	v_mov_b32_e32 v218, 1.0
	s_nop 0
	v_permlane32_swap_b32_e32 v177, v0
	v_max_f32_e32 v177, v177, v0
	v_cmp_ge_f32_e32 vcc, s90, v177
	s_cmp_eq_u64 vcc, exec
	s_cbranch_scc0 .Lmla_h1_newmax
; __device__ __forceinline__ void finishSM9(f32x16& p0, f32x16& p1, float alpha, float& l_reg, v8i32& p8) {
; #pragma unroll
;   for (int r = 0; r < 16; ++r) { p0[r] = __builtin_amdgcn_exp2f(p0[r]); p1[r] = __builtin_amdgcn_exp2f(p1[r]); }
;   float ps = 0;
; #pragma unroll
;   for (int r = 0; r < 16; ++r) ps += p0[r];
; #pragma unroll
;   for (int r = 0; r < 16; ++r) ps += p1[r];
;   { auto rr = __builtin_amdgcn_permlane32_swap(__float_as_uint(ps), __float_as_uint(ps), false, false);
;     ps = __uint_as_float(rr[0]) + __uint_as_float(rr[1]); }
;   l_reg = l_reg * alpha + ps;
; #pragma unroll
;   for (int g = 0; g < 4; ++g) {
;     int w = __builtin_amdgcn_cvt_pk_fp8_f32(p0[4 * g], p0[4 * g + 1], 0, false); p8[g] = __builtin_amdgcn_cvt_pk_fp8_f32(p0[4 * g + 2], p0[4 * g + 3], w, true);
;     int u = __builtin_amdgcn_cvt_pk_fp8_f32(p1[4 * g], p1[4 * g + 1], 0, false); p8[4 + g] = __builtin_amdgcn_cvt_pk_fp8_f32(p1[4 * g + 2], p1[4 * g + 3], u, true); }
; }
; __device__ __forceinline__ void pv8(f32x16* o, const char* Vt, const v8i32 p8, int r32, int hi) {
;   const int sw = (r32 >> 2) & 3, a0 = r32 * 64 + (((hi * 2) ^ sw) << 4), a1 = r32 * 64 + (((hi * 2 + 1) ^ sw) << 4);
; #pragma unroll
;   for (int d0 = 0; d0 < 4; ++d0) {
;     const v8i32 vf = cat8(*reinterpret_cast<const v4i32*>(Vt + d0 * 2048 + a0), *reinterpret_cast<const v4i32*>(Vt + d0 * 2048 + a1));
;     o[d0] = __builtin_amdgcn_mfma_scale_f32_32x32x64_f8f6f4(p8, vf, o[d0], 0, 0, 0, 127, 0, 127); }
; }
; __device__ __forceinline__ void qkt9(f32x16& p0, f32x16& p1, const char* Kn, const char* Kr, const v8i32* qf, const float init, int r32, int hi) {
; #pragma unroll
;   for (int r = 0; r < 16; ++r) { p0[r] = init; p1[r] = init; }
; #pragma unroll
;   for (int s = 0; s < 2; ++s) { const int c0 = s * 4 + hi * 2;
;     const v8i32 a0 = cat8(*reinterpret_cast<const v4i32*>(Kn + KN8SW(r32, c0)), *reinterpret_cast<const v4i32*>(Kn + KN8SW(r32, c0 + 1)));
;     const v8i32 a1 = cat8(*reinterpret_cast<const v4i32*>(Kn + 4096 + KN8SW(r32, c0)), *reinterpret_cast<const v4i32*>(Kn + 4096 + KN8SW(r32, c0 + 1)));
;     p0 = __builtin_amdgcn_mfma_scale_f32_32x32x64_f8f6f4(a0, qf[s], p0, 0, 0, 0, 127, 0, 124);
;     p1 = __builtin_amdgcn_mfma_scale_f32_32x32x64_f8f6f4(a1, qf[s], p1, 0, 0, 0, 127, 0, 124); }
;   { const int c0 = hi * 2;
.Lmla_h1_cont:
	ds_read_b128 v[114:117], v215 offset:16384
	ds_read_b128 v[118:121], v216 offset:16384
	ds_read_b128 v[222:225], v215 offset:20480
	ds_read_b128 v[226:229], v216 offset:20480
	v_exp_f32_e32 v0, v82
	v_exp_f32_e32 v177, v83
	v_exp_f32_e32 v179, v84
	v_exp_f32_e32 v254, v85
	v_add_f32_e32 v219, v0, v177
	v_cvt_pk_fp8_f32 v246, v0, v177
	v_add_f32_e32 v219, v179, v219
	v_add_f32_e32 v219, v254, v219
	v_cvt_pk_fp8_f32 v246, v179, v254 op_sel:[0,0,1]
	s_waitcnt lgkmcnt(2)
	v_mfma_scale_f32_32x32x64_f8f6f4 v[114:129], v[114:121], v[146:153], v[230:245], v194, v193 op_sel_hi:[0,0,0]
	global_load_dwordx4 v[158:161], v176, s[18:19]
	global_load_dwordx4 v[162:165], v178, s[16:17]
	global_load_dwordx4 v[154:157], v[180:181], off
	v_add_u32_e32 v176, 0x2000, v176
	v_add_u32_e32 v178, 0x20000, v178
	s_mov_b64 s[20:21], 0x1000
	v_lshl_add_u64 v[180:181], v[180:181], 0, s[20:21]
	v_exp_f32_e32 v0, v86
	v_exp_f32_e32 v177, v87
	v_exp_f32_e32 v179, v88
	v_exp_f32_e32 v254, v89
	v_add_f32_e32 v219, v0, v219
	v_add_f32_e32 v219, v177, v219
	v_cvt_pk_fp8_f32 v247, v0, v177
	v_add_f32_e32 v219, v179, v219
	v_add_f32_e32 v219, v254, v219
	v_cvt_pk_fp8_f32 v247, v179, v254 op_sel:[0,0,1]
	ds_read_b128 v[82:85], v213 offset:16384
	ds_read_b128 v[86:89], v214 offset:16384
	s_waitcnt lgkmcnt(2)
	v_mfma_scale_f32_32x32x64_f8f6f4 v[98:113], v[222:229], v[146:153], v[230:245], v194, v193 op_sel_hi:[0,0,0]
	ds_read_b128 v[222:225], v213 offset:20480
	ds_read_b128 v[226:229], v214 offset:20480
	v_exp_f32_e32 v0, v90
	v_exp_f32_e32 v177, v91
	v_exp_f32_e32 v179, v92
	v_exp_f32_e32 v254, v93
	v_add_f32_e32 v219, v0, v219
	v_add_f32_e32 v219, v177, v219
	v_cvt_pk_fp8_f32 v248, v0, v177
	v_add_f32_e32 v219, v179, v219
	v_add_f32_e32 v219, v254, v219
	v_cvt_pk_fp8_f32 v248, v179, v254 op_sel:[0,0,1]
	v_exp_f32_e32 v0, v94
	v_exp_f32_e32 v177, v95
	v_exp_f32_e32 v179, v96
	v_exp_f32_e32 v254, v97
	v_add_f32_e32 v219, v0, v219
	v_add_f32_e32 v219, v177, v219
	v_cvt_pk_fp8_f32 v249, v0, v177
	v_add_f32_e32 v219, v179, v219
	v_add_f32_e32 v219, v254, v219
	v_cvt_pk_fp8_f32 v249, v179, v254 op_sel:[0,0,1]
	ds_read_b128 v[90:93], v185 offset:32768
	ds_read_b128 v[94:97], v186 offset:32768
	s_waitcnt lgkmcnt(4)
	v_mfma_scale_f32_32x32x64_f8f6f4 v[114:129], v[82:89], v[138:145], v[114:129], v194, v193 op_sel_hi:[0,0,0]
	v_exp_f32_e32 v0, v66
	v_exp_f32_e32 v177, v67
	v_exp_f32_e32 v179, v68
	v_exp_f32_e32 v254, v69
	v_add_f32_e32 v219, v0, v219
	v_add_f32_e32 v219, v177, v219
	v_cvt_pk_fp8_f32 v250, v0, v177
	v_add_f32_e32 v219, v179, v219
	v_add_f32_e32 v219, v254, v219
	v_cvt_pk_fp8_f32 v250, v179, v254 op_sel:[0,0,1]
	s_waitcnt lgkmcnt(2)
	v_mfma_scale_f32_32x32x64_f8f6f4 v[98:113], v[222:229], v[138:145], v[98:113], v194, v193 op_sel_hi:[0,0,0]
	ds_read_b128 v[222:225], v185 offset:34816
	ds_read_b128 v[226:229], v186 offset:34816
	v_exp_f32_e32 v0, v70
	v_exp_f32_e32 v177, v71
	v_exp_f32_e32 v179, v72
	v_exp_f32_e32 v254, v73
	v_add_f32_e32 v219, v0, v219
	v_add_f32_e32 v219, v177, v219
	v_cvt_pk_fp8_f32 v251, v0, v177
	v_add_f32_e32 v219, v179, v219
	v_add_f32_e32 v219, v254, v219
	v_cvt_pk_fp8_f32 v251, v179, v254 op_sel:[0,0,1]
	v_exp_f32_e32 v0, v74
	v_exp_f32_e32 v177, v75
	v_exp_f32_e32 v179, v76
	v_exp_f32_e32 v254, v77
	v_add_f32_e32 v219, v0, v219
	v_add_f32_e32 v219, v177, v219
	v_cvt_pk_fp8_f32 v252, v0, v177
	v_add_f32_e32 v219, v179, v219
	v_add_f32_e32 v219, v254, v219
	v_cvt_pk_fp8_f32 v252, v179, v254 op_sel:[0,0,1]
	s_waitcnt lgkmcnt(2)
	v_mfma_scale_f32_32x32x64_f8f6f4 v[114:129], v[90:97], v[130:137], v[114:129], v194, v193 op_sel_hi:[0,0,0]
	v_exp_f32_e32 v0, v78
	v_exp_f32_e32 v177, v79
	v_exp_f32_e32 v179, v80
	v_exp_f32_e32 v254, v81
	v_add_f32_e32 v219, v0, v219
	v_add_f32_e32 v219, v177, v219
	v_cvt_pk_fp8_f32 v253, v0, v177
	v_add_f32_e32 v219, v179, v219
	v_add_f32_e32 v219, v254, v219
	v_cvt_pk_fp8_f32 v253, v179, v254 op_sel:[0,0,1]
	ds_read_b128 v[90:93], v185 offset:43008
	ds_read_b128 v[94:97], v186 offset:43008
	ds_read_b128 v[82:85], v185 offset:45056
	ds_read_b128 v[86:89], v186 offset:45056
	ds_read_b128 v[74:77], v185 offset:47104
	ds_read_b128 v[78:81], v186 offset:47104
	ds_read_b128 v[66:69], v185 offset:49152
	ds_read_b128 v[70:73], v186 offset:49152
	s_waitcnt lgkmcnt(8)
	v_mfma_scale_f32_32x32x64_f8f6f4 v[98:113], v[222:229], v[130:137], v[98:113], v194, v193 op_sel_hi:[0,0,0]
	v_mov_b32_e32 v0, v219
	s_nop 1
	v_permlane32_swap_b32_e32 v219, v0
	v_add_f32_e32 v219, v219, v0
	v_fma_f32 v209, v209, v218, v219
	v_max_f32_e32 v177, v114, v115
	v_max3_f32 v177, v177, v116, v117
	v_max3_f32 v177, v177, v118, v119
	v_max3_f32 v177, v177, v120, v121
	v_max3_f32 v177, v177, v122, v123
	v_max3_f32 v177, v177, v124, v125
	v_max3_f32 v177, v177, v126, v127
	v_max3_f32 v177, v177, v128, v129
	s_waitcnt lgkmcnt(6)
	v_mfma_scale_f32_32x32x64_f8f6f4 v[50:65], v[246:253], v[90:97], v[50:65], v194, v194 op_sel_hi:[0,0,0]
	s_waitcnt lgkmcnt(4)
	v_mfma_scale_f32_32x32x64_f8f6f4 v[34:49], v[246:253], v[82:89], v[34:49], v194, v194 op_sel_hi:[0,0,0]
	s_waitcnt lgkmcnt(2)
	v_mfma_scale_f32_32x32x64_f8f6f4 v[18:33], v[246:253], v[74:81], v[18:33], v194, v194 op_sel_hi:[0,0,0]
	s_waitcnt vmcnt(0)
	ds_write_b128 v210, v[158:161] offset:8192
	ds_write_b128 v211, v[162:165] offset:24576
	ds_write_b128 v212, v[154:157] offset:36864
	s_waitcnt lgkmcnt(3)
	v_mfma_scale_f32_32x32x64_f8f6f4 v[2:17], v[246:253], v[66:73], v[2:17], v194, v194 op_sel_hi:[0,0,0]
	s_waitcnt lgkmcnt(0)
	s_barrier
	v_max_f32_e32 v0, v98, v99
	v_max3_f32 v0, v0, v100, v101
	v_max3_f32 v0, v0, v102, v103
	v_max3_f32 v0, v0, v104, v105
	v_max3_f32 v0, v0, v106, v107
	v_max3_f32 v0, v0, v108, v109
	v_max3_f32 v0, v0, v110, v111
	v_max3_f32 v0, v0, v112, v113
	v_max_f32_e32 v177, v177, v0
	v_mov_b32_e32 v0, v177
	v_mov_b32_e32 v221, 1.0
	s_nop 0
	v_permlane32_swap_b32_e32 v177, v0
	v_max_f32_e32 v177, v177, v0
	v_cmp_ge_f32_e32 vcc, s90, v177
	s_cmp_eq_u64 vcc, exec
	s_cbranch_scc0 .Lmla_h2_newmax
; __device__ __forceinline__ void finishSM9(f32x16& p0, f32x16& p1, float alpha, float& l_reg, v8i32& p8) {
; #pragma unroll
;   for (int r = 0; r < 16; ++r) { p0[r] = __builtin_amdgcn_exp2f(p0[r]); p1[r] = __builtin_amdgcn_exp2f(p1[r]); }
;   float ps = 0;
; #pragma unroll
;   for (int r = 0; r < 16; ++r) ps += p0[r];
; #pragma unroll
;   for (int r = 0; r < 16; ++r) ps += p1[r];
;   { auto rr = __builtin_amdgcn_permlane32_swap(__float_as_uint(ps), __float_as_uint(ps), false, false);
;     ps = __uint_as_float(rr[0]) + __uint_as_float(rr[1]); }
;   l_reg = l_reg * alpha + ps;
; #pragma unroll
;   for (int g = 0; g < 4; ++g) {
;     int w = __builtin_amdgcn_cvt_pk_fp8_f32(p0[4 * g], p0[4 * g + 1], 0, false); p8[g] = __builtin_amdgcn_cvt_pk_fp8_f32(p0[4 * g + 2], p0[4 * g + 3], w, true);
;     int u = __builtin_amdgcn_cvt_pk_fp8_f32(p1[4 * g], p1[4 * g + 1], 0, false); p8[4 + g] = __builtin_amdgcn_cvt_pk_fp8_f32(p1[4 * g + 2], p1[4 * g + 3], u, true); }
; }
; __device__ __forceinline__ void pv8(f32x16* o, const char* Vt, const v8i32 p8, int r32, int hi) {
;   const int sw = (r32 >> 2) & 3, a0 = r32 * 64 + (((hi * 2) ^ sw) << 4), a1 = r32 * 64 + (((hi * 2 + 1) ^ sw) << 4);
; #pragma unroll
;   for (int d0 = 0; d0 < 4; ++d0) {
;     const v8i32 vf = cat8(*reinterpret_cast<const v4i32*>(Vt + d0 * 2048 + a0), *reinterpret_cast<const v4i32*>(Vt + d0 * 2048 + a1));
;     o[d0] = __builtin_amdgcn_mfma_scale_f32_32x32x64_f8f6f4(p8, vf, o[d0], 0, 0, 0, 127, 0, 127); }
; }
; __device__ __forceinline__ void qkt9(f32x16& p0, f32x16& p1, const char* Kn, const char* Kr, const v8i32* qf, const float init, int r32, int hi) {
; #pragma unroll
;   for (int r = 0; r < 16; ++r) { p0[r] = init; p1[r] = init; }
; #pragma unroll
;   for (int s = 0; s < 2; ++s) { const int c0 = s * 4 + hi * 2;
;     const v8i32 a0 = cat8(*reinterpret_cast<const v4i32*>(Kn + KN8SW(r32, c0)), *reinterpret_cast<const v4i32*>(Kn + KN8SW(r32, c0 + 1)));
;     const v8i32 a1 = cat8(*reinterpret_cast<const v4i32*>(Kn + 4096 + KN8SW(r32, c0)), *reinterpret_cast<const v4i32*>(Kn + 4096 + KN8SW(r32, c0 + 1)));
;     p0 = __builtin_amdgcn_mfma_scale_f32_32x32x64_f8f6f4(a0, qf[s], p0, 0, 0, 0, 127, 0, 124);
;     p1 = __builtin_amdgcn_mfma_scale_f32_32x32x64_f8f6f4(a1, qf[s], p1, 0, 0, 0, 127, 0, 124); }
;   { const int c0 = hi * 2;
.Lmla_h2_cont:
	ds_read_b128 v[82:85], v215 offset:24576
	ds_read_b128 v[86:89], v216 offset:24576
	ds_read_b128 v[222:225], v215 offset:28672
	ds_read_b128 v[226:229], v216 offset:28672
	v_exp_f32_e32 v0, v114
	v_exp_f32_e32 v177, v115
	v_exp_f32_e32 v179, v116
	v_exp_f32_e32 v254, v117
	v_add_f32_e32 v219, v0, v177
	v_cvt_pk_fp8_f32 v246, v0, v177
	v_add_f32_e32 v219, v179, v219
	v_add_f32_e32 v219, v254, v219
	v_cvt_pk_fp8_f32 v246, v179, v254 op_sel:[0,0,1]
	s_waitcnt lgkmcnt(2)
	v_mfma_scale_f32_32x32x64_f8f6f4 v[82:97], v[82:89], v[146:153], v[230:245], v194, v193 op_sel_hi:[0,0,0]
	global_load_dwordx4 v[158:161], v176, s[18:19]
	global_load_dwordx4 v[162:165], v178, s[16:17]
	global_load_dwordx4 v[154:157], v[180:181], off
	v_add_u32_e32 v176, 0x2000, v176
	v_add_u32_e32 v178, 0x20000, v178
	s_mov_b64 s[20:21], 0x1000
	v_lshl_add_u64 v[180:181], v[180:181], 0, s[20:21]
	v_exp_f32_e32 v0, v118
	v_exp_f32_e32 v177, v119
	v_exp_f32_e32 v179, v120
	v_exp_f32_e32 v254, v121
	v_add_f32_e32 v219, v0, v219
	v_add_f32_e32 v219, v177, v219
	v_cvt_pk_fp8_f32 v247, v0, v177
	v_add_f32_e32 v219, v179, v219
	v_add_f32_e32 v219, v254, v219
	v_cvt_pk_fp8_f32 v247, v179, v254 op_sel:[0,0,1]
	ds_read_b128 v[114:117], v213 offset:24576
	ds_read_b128 v[118:121], v214 offset:24576
	s_waitcnt lgkmcnt(2)
	v_mfma_scale_f32_32x32x64_f8f6f4 v[66:81], v[222:229], v[146:153], v[230:245], v194, v193 op_sel_hi:[0,0,0]
	ds_read_b128 v[222:225], v213 offset:28672
	ds_read_b128 v[226:229], v214 offset:28672
	v_exp_f32_e32 v0, v122
	v_exp_f32_e32 v177, v123
	v_exp_f32_e32 v179, v124
	v_exp_f32_e32 v254, v125
	v_add_f32_e32 v219, v0, v219
	v_add_f32_e32 v219, v177, v219
	v_cvt_pk_fp8_f32 v248, v0, v177
	v_add_f32_e32 v219, v179, v219
	v_add_f32_e32 v219, v254, v219
	v_cvt_pk_fp8_f32 v248, v179, v254 op_sel:[0,0,1]
	v_exp_f32_e32 v0, v126
	v_exp_f32_e32 v177, v127
	v_exp_f32_e32 v179, v128
	v_exp_f32_e32 v254, v129
	v_add_f32_e32 v219, v0, v219
	v_add_f32_e32 v219, v177, v219
	v_cvt_pk_fp8_f32 v249, v0, v177
	v_add_f32_e32 v219, v179, v219
	v_add_f32_e32 v219, v254, v219
	v_cvt_pk_fp8_f32 v249, v179, v254 op_sel:[0,0,1]
	ds_read_b128 v[122:125], v185 offset:36864
	ds_read_b128 v[126:129], v186 offset:36864
	s_waitcnt lgkmcnt(4)
	v_mfma_scale_f32_32x32x64_f8f6f4 v[82:97], v[114:121], v[138:145], v[82:97], v194, v193 op_sel_hi:[0,0,0]
	v_exp_f32_e32 v0, v98
	v_exp_f32_e32 v177, v99
	v_exp_f32_e32 v179, v100
	v_exp_f32_e32 v254, v101
	v_add_f32_e32 v219, v0, v219
	v_add_f32_e32 v219, v177, v219
	v_cvt_pk_fp8_f32 v250, v0, v177
	v_add_f32_e32 v219, v179, v219
	v_add_f32_e32 v219, v254, v219
	v_cvt_pk_fp8_f32 v250, v179, v254 op_sel:[0,0,1]
	s_waitcnt lgkmcnt(2)
	v_mfma_scale_f32_32x32x64_f8f6f4 v[66:81], v[222:229], v[138:145], v[66:81], v194, v193 op_sel_hi:[0,0,0]
	ds_read_b128 v[222:225], v185 offset:38912
	ds_read_b128 v[226:229], v186 offset:38912
	v_exp_f32_e32 v0, v102
	v_exp_f32_e32 v177, v103
	v_exp_f32_e32 v179, v104
	v_exp_f32_e32 v254, v105
	v_add_f32_e32 v219, v0, v219
	v_add_f32_e32 v219, v177, v219
	v_cvt_pk_fp8_f32 v251, v0, v177
	v_add_f32_e32 v219, v179, v219
	v_add_f32_e32 v219, v254, v219
	v_cvt_pk_fp8_f32 v251, v179, v254 op_sel:[0,0,1]
	v_exp_f32_e32 v0, v106
	v_exp_f32_e32 v177, v107
	v_exp_f32_e32 v179, v108
	v_exp_f32_e32 v254, v109
	v_add_f32_e32 v219, v0, v219
	v_add_f32_e32 v219, v177, v219
	v_cvt_pk_fp8_f32 v252, v0, v177
	v_add_f32_e32 v219, v179, v219
	v_add_f32_e32 v219, v254, v219
	v_cvt_pk_fp8_f32 v252, v179, v254 op_sel:[0,0,1]
	s_waitcnt lgkmcnt(2)
	v_mfma_scale_f32_32x32x64_f8f6f4 v[82:97], v[122:129], v[130:137], v[82:97], v194, v193 op_sel_hi:[0,0,0]
	v_exp_f32_e32 v0, v110
	v_exp_f32_e32 v177, v111
	v_exp_f32_e32 v179, v112
	v_exp_f32_e32 v254, v113
	v_add_f32_e32 v219, v0, v219
	v_add_f32_e32 v219, v177, v219
	v_cvt_pk_fp8_f32 v253, v0, v177
	v_add_f32_e32 v219, v179, v219
	v_add_f32_e32 v219, v254, v219
	v_cvt_pk_fp8_f32 v253, v179, v254 op_sel:[0,0,1]
	ds_read_b128 v[122:125], v185 offset:0
	ds_read_b128 v[126:129], v186 offset:0
	ds_read_b128 v[114:117], v185 offset:2048
	ds_read_b128 v[118:121], v186 offset:2048
	ds_read_b128 v[106:109], v185 offset:4096
	ds_read_b128 v[110:113], v186 offset:4096
	ds_read_b128 v[98:101], v185 offset:6144
	ds_read_b128 v[102:105], v186 offset:6144
	s_waitcnt lgkmcnt(8)
	v_mfma_scale_f32_32x32x64_f8f6f4 v[66:81], v[222:229], v[130:137], v[66:81], v194, v193 op_sel_hi:[0,0,0]
	v_mov_b32_e32 v0, v219
	s_nop 1
	v_permlane32_swap_b32_e32 v219, v0
	v_add_f32_e32 v219, v219, v0
	v_fma_f32 v209, v209, v221, v219
	v_max_f32_e32 v177, v82, v83
	v_max3_f32 v177, v177, v84, v85
	v_max3_f32 v177, v177, v86, v87
	v_max3_f32 v177, v177, v88, v89
	v_max3_f32 v177, v177, v90, v91
	v_max3_f32 v177, v177, v92, v93
	v_max3_f32 v177, v177, v94, v95
	v_max3_f32 v177, v177, v96, v97
	s_waitcnt lgkmcnt(6)
	v_mfma_scale_f32_32x32x64_f8f6f4 v[50:65], v[246:253], v[122:129], v[50:65], v194, v194 op_sel_hi:[0,0,0]
	s_waitcnt lgkmcnt(4)
	v_mfma_scale_f32_32x32x64_f8f6f4 v[34:49], v[246:253], v[114:121], v[34:49], v194, v194 op_sel_hi:[0,0,0]
	s_waitcnt lgkmcnt(2)
	v_mfma_scale_f32_32x32x64_f8f6f4 v[18:33], v[246:253], v[106:113], v[18:33], v194, v194 op_sel_hi:[0,0,0]
	s_waitcnt vmcnt(0)
	ds_write_b128 v210, v[158:161] offset:43008
	ds_write_b128 v211, v[162:165] offset:51200
	ds_write_b128 v212, v[154:157] offset:59392
	s_waitcnt lgkmcnt(3)
	v_mfma_scale_f32_32x32x64_f8f6f4 v[2:17], v[246:253], v[98:105], v[2:17], v194, v194 op_sel_hi:[0,0,0]
	s_waitcnt lgkmcnt(0)
	s_barrier
	v_max_f32_e32 v0, v66, v67
	v_max3_f32 v0, v0, v68, v69
	v_max3_f32 v0, v0, v70, v71
	v_max3_f32 v0, v0, v72, v73
	v_max3_f32 v0, v0, v74, v75
	v_max3_f32 v0, v0, v76, v77
	v_max3_f32 v0, v0, v78, v79
	v_max3_f32 v0, v0, v80, v81
	v_max_f32_e32 v177, v177, v0
	v_mov_b32_e32 v0, v177
	v_mov_b32_e32 v218, 1.0
	s_nop 0
	v_permlane32_swap_b32_e32 v177, v0
	v_max_f32_e32 v177, v177, v0
	v_cmp_ge_f32_e32 vcc, s90, v177
	s_cmp_eq_u64 vcc, exec
	s_cbranch_scc0 .Lmla_h3_newmax
; __device__ __forceinline__ void finishSM9(f32x16& p0, f32x16& p1, float alpha, float& l_reg, v8i32& p8) {
; #pragma unroll
;   for (int r = 0; r < 16; ++r) { p0[r] = __builtin_amdgcn_exp2f(p0[r]); p1[r] = __builtin_amdgcn_exp2f(p1[r]); }
;   float ps = 0;
; #pragma unroll
;   for (int r = 0; r < 16; ++r) ps += p0[r];
; #pragma unroll
;   for (int r = 0; r < 16; ++r) ps += p1[r];
;   { auto rr = __builtin_amdgcn_permlane32_swap(__float_as_uint(ps), __float_as_uint(ps), false, false);
;     ps = __uint_as_float(rr[0]) + __uint_as_float(rr[1]); }
;   l_reg = l_reg * alpha + ps;
; #pragma unroll
;   for (int g = 0; g < 4; ++g) {
;     int w = __builtin_amdgcn_cvt_pk_fp8_f32(p0[4 * g], p0[4 * g + 1], 0, false); p8[g] = __builtin_amdgcn_cvt_pk_fp8_f32(p0[4 * g + 2], p0[4 * g + 3], w, true);
;     int u = __builtin_amdgcn_cvt_pk_fp8_f32(p1[4 * g], p1[4 * g + 1], 0, false); p8[4 + g] = __builtin_amdgcn_cvt_pk_fp8_f32(p1[4 * g + 2], p1[4 * g + 3], u, true); }
; }
; __device__ __forceinline__ void pv8(f32x16* o, const char* Vt, const v8i32 p8, int r32, int hi) {
;   const int sw = (r32 >> 2) & 3, a0 = r32 * 64 + (((hi * 2) ^ sw) << 4), a1 = r32 * 64 + (((hi * 2 + 1) ^ sw) << 4);
; #pragma unroll
;   for (int d0 = 0; d0 < 4; ++d0) {
;     const v8i32 vf = cat8(*reinterpret_cast<const v4i32*>(Vt + d0 * 2048 + a0), *reinterpret_cast<const v4i32*>(Vt + d0 * 2048 + a1));
;     o[d0] = __builtin_amdgcn_mfma_scale_f32_32x32x64_f8f6f4(p8, vf, o[d0], 0, 0, 0, 127, 0, 127); }
; }
; __device__ __forceinline__ void qkt9(f32x16& p0, f32x16& p1, const char* Kn, const char* Kr, const v8i32* qf, const float init, int r32, int hi) {
; #pragma unroll
;   for (int r = 0; r < 16; ++r) { p0[r] = init; p1[r] = init; }
; #pragma unroll
;   for (int s = 0; s < 2; ++s) { const int c0 = s * 4 + hi * 2;
;     const v8i32 a0 = cat8(*reinterpret_cast<const v4i32*>(Kn + KN8SW(r32, c0)), *reinterpret_cast<const v4i32*>(Kn + KN8SW(r32, c0 + 1)));
;     const v8i32 a1 = cat8(*reinterpret_cast<const v4i32*>(Kn + 4096 + KN8SW(r32, c0)), *reinterpret_cast<const v4i32*>(Kn + 4096 + KN8SW(r32, c0 + 1)));
;     p0 = __builtin_amdgcn_mfma_scale_f32_32x32x64_f8f6f4(a0, qf[s], p0, 0, 0, 0, 127, 0, 124);
;     p1 = __builtin_amdgcn_mfma_scale_f32_32x32x64_f8f6f4(a1, qf[s], p1, 0, 0, 0, 127, 0, 124); }
;   { const int c0 = hi * 2;
.Lmla_h3_cont:
	ds_read_b128 v[114:117], v215 offset:51200
	ds_read_b128 v[118:121], v216 offset:51200
	ds_read_b128 v[222:225], v215 offset:55296
	ds_read_b128 v[226:229], v216 offset:55296
	v_exp_f32_e32 v0, v82
	v_exp_f32_e32 v177, v83
	v_exp_f32_e32 v179, v84
	v_exp_f32_e32 v254, v85
	v_add_f32_e32 v219, v0, v177
	v_cvt_pk_fp8_f32 v246, v0, v177
	v_add_f32_e32 v219, v179, v219
	v_add_f32_e32 v219, v254, v219
	v_cvt_pk_fp8_f32 v246, v179, v254 op_sel:[0,0,1]
	s_waitcnt lgkmcnt(2)
	v_mfma_scale_f32_32x32x64_f8f6f4 v[114:129], v[114:121], v[146:153], v[230:245], v194, v193 op_sel_hi:[0,0,0]
	global_load_dwordx4 v[158:161], v176, s[18:19]
	global_load_dwordx4 v[162:165], v178, s[16:17]
	global_load_dwordx4 v[154:157], v[180:181], off
	v_add_u32_e32 v176, 0x2000, v176
	v_add_u32_e32 v178, 0x20000, v178
	s_mov_b64 s[20:21], 0x1000
	v_lshl_add_u64 v[180:181], v[180:181], 0, s[20:21]
	v_exp_f32_e32 v0, v86
	v_exp_f32_e32 v177, v87
	v_exp_f32_e32 v179, v88
	v_exp_f32_e32 v254, v89
	v_add_f32_e32 v219, v0, v219
	v_add_f32_e32 v219, v177, v219
	v_cvt_pk_fp8_f32 v247, v0, v177
	v_add_f32_e32 v219, v179, v219
	v_add_f32_e32 v219, v254, v219
	v_cvt_pk_fp8_f32 v247, v179, v254 op_sel:[0,0,1]
	ds_read_b128 v[82:85], v213 offset:51200
	ds_read_b128 v[86:89], v214 offset:51200
	s_waitcnt lgkmcnt(2)
	v_mfma_scale_f32_32x32x64_f8f6f4 v[98:113], v[222:229], v[146:153], v[230:245], v194, v193 op_sel_hi:[0,0,0]
	ds_read_b128 v[222:225], v213 offset:55296
	ds_read_b128 v[226:229], v214 offset:55296
	v_exp_f32_e32 v0, v90
	v_exp_f32_e32 v177, v91
	v_exp_f32_e32 v179, v92
	v_exp_f32_e32 v254, v93
	v_add_f32_e32 v219, v0, v219
	v_add_f32_e32 v219, v177, v219
	v_cvt_pk_fp8_f32 v248, v0, v177
	v_add_f32_e32 v219, v179, v219
	v_add_f32_e32 v219, v254, v219
	v_cvt_pk_fp8_f32 v248, v179, v254 op_sel:[0,0,1]
	v_exp_f32_e32 v0, v94
	v_exp_f32_e32 v177, v95
	v_exp_f32_e32 v179, v96
	v_exp_f32_e32 v254, v97
	v_add_f32_e32 v219, v0, v219
	v_add_f32_e32 v219, v177, v219
	v_cvt_pk_fp8_f32 v249, v0, v177
	v_add_f32_e32 v219, v179, v219
	v_add_f32_e32 v219, v254, v219
	v_cvt_pk_fp8_f32 v249, v179, v254 op_sel:[0,0,1]
	ds_read_b128 v[90:93], v185 offset:59392
	ds_read_b128 v[94:97], v186 offset:59392
	s_waitcnt lgkmcnt(4)
	v_mfma_scale_f32_32x32x64_f8f6f4 v[114:129], v[82:89], v[138:145], v[114:129], v194, v193 op_sel_hi:[0,0,0]
	v_exp_f32_e32 v0, v66
	v_exp_f32_e32 v177, v67
	v_exp_f32_e32 v179, v68
	v_exp_f32_e32 v254, v69
	v_add_f32_e32 v219, v0, v219
	v_add_f32_e32 v219, v177, v219
	v_cvt_pk_fp8_f32 v250, v0, v177
	v_add_f32_e32 v219, v179, v219
	v_add_f32_e32 v219, v254, v219
	v_cvt_pk_fp8_f32 v250, v179, v254 op_sel:[0,0,1]
	s_waitcnt lgkmcnt(2)
	v_mfma_scale_f32_32x32x64_f8f6f4 v[98:113], v[222:229], v[138:145], v[98:113], v194, v193 op_sel_hi:[0,0,0]
	ds_read_b128 v[222:225], v185 offset:61440
	ds_read_b128 v[226:229], v186 offset:61440
	v_exp_f32_e32 v0, v70
	v_exp_f32_e32 v177, v71
	v_exp_f32_e32 v179, v72
	v_exp_f32_e32 v254, v73
	v_add_f32_e32 v219, v0, v219
	v_add_f32_e32 v219, v177, v219
	v_cvt_pk_fp8_f32 v251, v0, v177
	v_add_f32_e32 v219, v179, v219
	v_add_f32_e32 v219, v254, v219
	v_cvt_pk_fp8_f32 v251, v179, v254 op_sel:[0,0,1]
	v_exp_f32_e32 v0, v74
	v_exp_f32_e32 v177, v75
	v_exp_f32_e32 v179, v76
	v_exp_f32_e32 v254, v77
	v_add_f32_e32 v219, v0, v219
	v_add_f32_e32 v219, v177, v219
	v_cvt_pk_fp8_f32 v252, v0, v177
	v_add_f32_e32 v219, v179, v219
	v_add_f32_e32 v219, v254, v219
	v_cvt_pk_fp8_f32 v252, v179, v254 op_sel:[0,0,1]
	s_waitcnt lgkmcnt(2)
	v_mfma_scale_f32_32x32x64_f8f6f4 v[114:129], v[90:97], v[130:137], v[114:129], v194, v193 op_sel_hi:[0,0,0]
	v_exp_f32_e32 v0, v78
	v_exp_f32_e32 v177, v79
	v_exp_f32_e32 v179, v80
	v_exp_f32_e32 v254, v81
	v_add_f32_e32 v219, v0, v219
	v_add_f32_e32 v219, v177, v219
	v_cvt_pk_fp8_f32 v253, v0, v177
	v_add_f32_e32 v219, v179, v219
	v_add_f32_e32 v219, v254, v219
	v_cvt_pk_fp8_f32 v253, v179, v254 op_sel:[0,0,1]
	ds_read_b128 v[90:93], v185 offset:8192
	ds_read_b128 v[94:97], v186 offset:8192
	ds_read_b128 v[82:85], v185 offset:10240
	ds_read_b128 v[86:89], v186 offset:10240
	ds_read_b128 v[74:77], v185 offset:12288
	ds_read_b128 v[78:81], v186 offset:12288
	ds_read_b128 v[66:69], v185 offset:14336
	ds_read_b128 v[70:73], v186 offset:14336
	s_waitcnt lgkmcnt(8)
	v_mfma_scale_f32_32x32x64_f8f6f4 v[98:113], v[222:229], v[130:137], v[98:113], v194, v193 op_sel_hi:[0,0,0]
	v_mov_b32_e32 v0, v219
	s_nop 1
	v_permlane32_swap_b32_e32 v219, v0
	v_add_f32_e32 v219, v219, v0
	v_fma_f32 v209, v209, v218, v219
	v_max_f32_e32 v177, v114, v115
	v_max3_f32 v177, v177, v116, v117
	v_max3_f32 v177, v177, v118, v119
	v_max3_f32 v177, v177, v120, v121
	v_max3_f32 v177, v177, v122, v123
	v_max3_f32 v177, v177, v124, v125
	v_max3_f32 v177, v177, v126, v127
	v_max3_f32 v177, v177, v128, v129
	s_waitcnt lgkmcnt(6)
	v_mfma_scale_f32_32x32x64_f8f6f4 v[50:65], v[246:253], v[90:97], v[50:65], v194, v194 op_sel_hi:[0,0,0]
	s_waitcnt lgkmcnt(4)
	v_mfma_scale_f32_32x32x64_f8f6f4 v[34:49], v[246:253], v[82:89], v[34:49], v194, v194 op_sel_hi:[0,0,0]
	s_waitcnt lgkmcnt(2)
	v_mfma_scale_f32_32x32x64_f8f6f4 v[18:33], v[246:253], v[74:81], v[18:33], v194, v194 op_sel_hi:[0,0,0]
	s_waitcnt vmcnt(0)
	ds_write_b128 v210, v[158:161]
	ds_write_b128 v211, v[162:165] offset:16384
	ds_write_b128 v212, v[154:157] offset:32768
	s_waitcnt lgkmcnt(3)
	v_mfma_scale_f32_32x32x64_f8f6f4 v[2:17], v[246:253], v[66:73], v[2:17], v194, v194 op_sel_hi:[0,0,0]
	s_waitcnt lgkmcnt(0)
	s_barrier
	v_max_f32_e32 v0, v98, v99
	v_max3_f32 v0, v0, v100, v101
	v_max3_f32 v0, v0, v102, v103
	v_max3_f32 v0, v0, v104, v105
	v_max3_f32 v0, v0, v106, v107
	v_max3_f32 v0, v0, v108, v109
	v_max3_f32 v0, v0, v110, v111
	v_max3_f32 v0, v0, v112, v113
	v_max_f32_e32 v177, v177, v0
	v_mov_b32_e32 v0, v177
	v_mov_b32_e32 v221, 1.0
	s_nop 0
	v_permlane32_swap_b32_e32 v177, v0
	v_max_f32_e32 v177, v177, v0
	v_cmp_ge_f32_e32 vcc, s90, v177
	s_cmp_eq_u64 vcc, exec
	s_cbranch_scc0 .Lmla_h4_newmax
; __device__ __forceinline__ void finishSM9(f32x16& p0, f32x16& p1, float alpha, float& l_reg, v8i32& p8) {
; #pragma unroll
;   for (int r = 0; r < 16; ++r) { p0[r] = __builtin_amdgcn_exp2f(p0[r]); p1[r] = __builtin_amdgcn_exp2f(p1[r]); }
;   float ps = 0;
; #pragma unroll
;   for (int r = 0; r < 16; ++r) ps += p0[r];
; #pragma unroll
;   for (int r = 0; r < 16; ++r) ps += p1[r];
;   { auto rr = __builtin_amdgcn_permlane32_swap(__float_as_uint(ps), __float_as_uint(ps), false, false);
;     ps = __uint_as_float(rr[0]) + __uint_as_float(rr[1]); }
;   l_reg = l_reg * alpha + ps;
; #pragma unroll
;   for (int g = 0; g < 4; ++g) {
;     int w = __builtin_amdgcn_cvt_pk_fp8_f32(p0[4 * g], p0[4 * g + 1], 0, false); p8[g] = __builtin_amdgcn_cvt_pk_fp8_f32(p0[4 * g + 2], p0[4 * g + 3], w, true);
;     int u = __builtin_amdgcn_cvt_pk_fp8_f32(p1[4 * g], p1[4 * g + 1], 0, false); p8[4 + g] = __builtin_amdgcn_cvt_pk_fp8_f32(p1[4 * g + 2], p1[4 * g + 3], u, true); }
; }
; __device__ __forceinline__ void pv8(f32x16* o, const char* Vt, const v8i32 p8, int r32, int hi) {
;   const int sw = (r32 >> 2) & 3, a0 = r32 * 64 + (((hi * 2) ^ sw) << 4), a1 = r32 * 64 + (((hi * 2 + 1) ^ sw) << 4);
; #pragma unroll
;   for (int d0 = 0; d0 < 4; ++d0) {
;     const v8i32 vf = cat8(*reinterpret_cast<const v4i32*>(Vt + d0 * 2048 + a0), *reinterpret_cast<const v4i32*>(Vt + d0 * 2048 + a1));
;     o[d0] = __builtin_amdgcn_mfma_scale_f32_32x32x64_f8f6f4(p8, vf, o[d0], 0, 0, 0, 127, 0, 127); }
; }
; __device__ __forceinline__ void qkt9(f32x16& p0, f32x16& p1, const char* Kn, const char* Kr, const v8i32* qf, const float init, int r32, int hi) {
; #pragma unroll
;   for (int r = 0; r < 16; ++r) { p0[r] = init; p1[r] = init; }
; #pragma unroll
;   for (int s = 0; s < 2; ++s) { const int c0 = s * 4 + hi * 2;
;     const v8i32 a0 = cat8(*reinterpret_cast<const v4i32*>(Kn + KN8SW(r32, c0)), *reinterpret_cast<const v4i32*>(Kn + KN8SW(r32, c0 + 1)));
;     const v8i32 a1 = cat8(*reinterpret_cast<const v4i32*>(Kn + 4096 + KN8SW(r32, c0)), *reinterpret_cast<const v4i32*>(Kn + 4096 + KN8SW(r32, c0 + 1)));
;     p0 = __builtin_amdgcn_mfma_scale_f32_32x32x64_f8f6f4(a0, qf[s], p0, 0, 0, 0, 127, 0, 124);
;     p1 = __builtin_amdgcn_mfma_scale_f32_32x32x64_f8f6f4(a1, qf[s], p1, 0, 0, 0, 127, 0, 124); }
;   { const int c0 = hi * 2;
.Lmla_h4_cont:
	ds_read_b128 v[82:85], v215 offset:16384
	ds_read_b128 v[86:89], v216 offset:16384
	ds_read_b128 v[222:225], v215 offset:20480
	ds_read_b128 v[226:229], v216 offset:20480
	v_exp_f32_e32 v0, v114
	v_exp_f32_e32 v177, v115
	v_exp_f32_e32 v179, v116
	v_exp_f32_e32 v254, v117
	v_add_f32_e32 v219, v0, v177
	v_cvt_pk_fp8_f32 v246, v0, v177
	v_add_f32_e32 v219, v179, v219
	v_add_f32_e32 v219, v254, v219
	v_cvt_pk_fp8_f32 v246, v179, v254 op_sel:[0,0,1]
	s_waitcnt lgkmcnt(2)
	v_mfma_scale_f32_32x32x64_f8f6f4 v[82:97], v[82:89], v[146:153], v[230:245], v194, v193 op_sel_hi:[0,0,0]
	global_load_dwordx4 v[158:161], v176, s[18:19]
	global_load_dwordx4 v[162:165], v178, s[16:17]
	global_load_dwordx4 v[154:157], v[180:181], off
	v_add_u32_e32 v176, 0x2000, v176
	v_add_u32_e32 v178, 0x20000, v178
	s_mov_b64 s[20:21], 0x1000
	v_lshl_add_u64 v[180:181], v[180:181], 0, s[20:21]
	v_exp_f32_e32 v0, v118
	v_exp_f32_e32 v177, v119
	v_exp_f32_e32 v179, v120
	v_exp_f32_e32 v254, v121
	v_add_f32_e32 v219, v0, v219
	v_add_f32_e32 v219, v177, v219
	v_cvt_pk_fp8_f32 v247, v0, v177
	v_add_f32_e32 v219, v179, v219
	v_add_f32_e32 v219, v254, v219
	v_cvt_pk_fp8_f32 v247, v179, v254 op_sel:[0,0,1]
	ds_read_b128 v[114:117], v213 offset:16384
	ds_read_b128 v[118:121], v214 offset:16384
	s_waitcnt lgkmcnt(2)
	v_mfma_scale_f32_32x32x64_f8f6f4 v[66:81], v[222:229], v[146:153], v[230:245], v194, v193 op_sel_hi:[0,0,0]
	ds_read_b128 v[222:225], v213 offset:20480
	ds_read_b128 v[226:229], v214 offset:20480
	v_exp_f32_e32 v0, v122
	v_exp_f32_e32 v177, v123
	v_exp_f32_e32 v179, v124
	v_exp_f32_e32 v254, v125
	v_add_f32_e32 v219, v0, v219
	v_add_f32_e32 v219, v177, v219
	v_cvt_pk_fp8_f32 v248, v0, v177
	v_add_f32_e32 v219, v179, v219
	v_add_f32_e32 v219, v254, v219
	v_cvt_pk_fp8_f32 v248, v179, v254 op_sel:[0,0,1]
	v_exp_f32_e32 v0, v126
	v_exp_f32_e32 v177, v127
	v_exp_f32_e32 v179, v128
	v_exp_f32_e32 v254, v129
	v_add_f32_e32 v219, v0, v219
	v_add_f32_e32 v219, v177, v219
	v_cvt_pk_fp8_f32 v249, v0, v177
	v_add_f32_e32 v219, v179, v219
	v_add_f32_e32 v219, v254, v219
	v_cvt_pk_fp8_f32 v249, v179, v254 op_sel:[0,0,1]
	ds_read_b128 v[122:125], v185 offset:32768
	ds_read_b128 v[126:129], v186 offset:32768
	s_waitcnt lgkmcnt(4)
	v_mfma_scale_f32_32x32x64_f8f6f4 v[82:97], v[114:121], v[138:145], v[82:97], v194, v193 op_sel_hi:[0,0,0]
	v_exp_f32_e32 v0, v98
	v_exp_f32_e32 v177, v99
	v_exp_f32_e32 v179, v100
	v_exp_f32_e32 v254, v101
	v_add_f32_e32 v219, v0, v219
	v_add_f32_e32 v219, v177, v219
	v_cvt_pk_fp8_f32 v250, v0, v177
	v_add_f32_e32 v219, v179, v219
	v_add_f32_e32 v219, v254, v219
	v_cvt_pk_fp8_f32 v250, v179, v254 op_sel:[0,0,1]
	s_waitcnt lgkmcnt(2)
	v_mfma_scale_f32_32x32x64_f8f6f4 v[66:81], v[222:229], v[138:145], v[66:81], v194, v193 op_sel_hi:[0,0,0]
	ds_read_b128 v[222:225], v185 offset:34816
	ds_read_b128 v[226:229], v186 offset:34816
	v_exp_f32_e32 v0, v102
	v_exp_f32_e32 v177, v103
	v_exp_f32_e32 v179, v104
	v_exp_f32_e32 v254, v105
	v_add_f32_e32 v219, v0, v219
	v_add_f32_e32 v219, v177, v219
	v_cvt_pk_fp8_f32 v251, v0, v177
	v_add_f32_e32 v219, v179, v219
	v_add_f32_e32 v219, v254, v219
	v_cvt_pk_fp8_f32 v251, v179, v254 op_sel:[0,0,1]
	v_exp_f32_e32 v0, v106
	v_exp_f32_e32 v177, v107
	v_exp_f32_e32 v179, v108
	v_exp_f32_e32 v254, v109
	v_add_f32_e32 v219, v0, v219
	v_add_f32_e32 v219, v177, v219
	v_cvt_pk_fp8_f32 v252, v0, v177
	v_add_f32_e32 v219, v179, v219
	v_add_f32_e32 v219, v254, v219
	v_cvt_pk_fp8_f32 v252, v179, v254 op_sel:[0,0,1]
	s_waitcnt lgkmcnt(2)
	v_mfma_scale_f32_32x32x64_f8f6f4 v[82:97], v[122:129], v[130:137], v[82:97], v194, v193 op_sel_hi:[0,0,0]
	v_exp_f32_e32 v0, v110
	v_exp_f32_e32 v177, v111
	v_exp_f32_e32 v179, v112
	v_exp_f32_e32 v254, v113
	v_add_f32_e32 v219, v0, v219
	v_add_f32_e32 v219, v177, v219
	v_cvt_pk_fp8_f32 v253, v0, v177
	v_add_f32_e32 v219, v179, v219
	v_add_f32_e32 v219, v254, v219
	v_cvt_pk_fp8_f32 v253, v179, v254 op_sel:[0,0,1]
	ds_read_b128 v[122:125], v185 offset:43008
	ds_read_b128 v[126:129], v186 offset:43008
	ds_read_b128 v[114:117], v185 offset:45056
	ds_read_b128 v[118:121], v186 offset:45056
	ds_read_b128 v[106:109], v185 offset:47104
	ds_read_b128 v[110:113], v186 offset:47104
	ds_read_b128 v[98:101], v185 offset:49152
	ds_read_b128 v[102:105], v186 offset:49152
	s_waitcnt lgkmcnt(8)
	v_mfma_scale_f32_32x32x64_f8f6f4 v[66:81], v[222:229], v[130:137], v[66:81], v194, v193 op_sel_hi:[0,0,0]
	v_mov_b32_e32 v0, v219
	s_nop 1
	v_permlane32_swap_b32_e32 v219, v0
	v_add_f32_e32 v219, v219, v0
	v_fma_f32 v209, v209, v221, v219
	v_max_f32_e32 v177, v82, v83
	v_max3_f32 v177, v177, v84, v85
	v_max3_f32 v177, v177, v86, v87
	v_max3_f32 v177, v177, v88, v89
	v_max3_f32 v177, v177, v90, v91
	v_max3_f32 v177, v177, v92, v93
	v_max3_f32 v177, v177, v94, v95
	v_max3_f32 v177, v177, v96, v97
	s_waitcnt lgkmcnt(6)
	v_mfma_scale_f32_32x32x64_f8f6f4 v[50:65], v[246:253], v[122:129], v[50:65], v194, v194 op_sel_hi:[0,0,0]
	s_waitcnt lgkmcnt(4)
	v_mfma_scale_f32_32x32x64_f8f6f4 v[34:49], v[246:253], v[114:121], v[34:49], v194, v194 op_sel_hi:[0,0,0]
	s_waitcnt lgkmcnt(2)
	v_mfma_scale_f32_32x32x64_f8f6f4 v[18:33], v[246:253], v[106:113], v[18:33], v194, v194 op_sel_hi:[0,0,0]
	s_waitcnt vmcnt(0)
	ds_write_b128 v210, v[158:161] offset:8192
	ds_write_b128 v211, v[162:165] offset:24576
	ds_write_b128 v212, v[154:157] offset:36864
	s_waitcnt lgkmcnt(3)
	v_mfma_scale_f32_32x32x64_f8f6f4 v[2:17], v[246:253], v[98:105], v[2:17], v194, v194 op_sel_hi:[0,0,0]
	s_waitcnt lgkmcnt(0)
	s_barrier
	v_max_f32_e32 v0, v66, v67
	v_max3_f32 v0, v0, v68, v69
	v_max3_f32 v0, v0, v70, v71
	v_max3_f32 v0, v0, v72, v73
	v_max3_f32 v0, v0, v74, v75
	v_max3_f32 v0, v0, v76, v77
	v_max3_f32 v0, v0, v78, v79
	v_max3_f32 v0, v0, v80, v81
	v_max_f32_e32 v177, v177, v0
	v_mov_b32_e32 v0, v177
	v_mov_b32_e32 v218, 1.0
	s_nop 0
	v_permlane32_swap_b32_e32 v177, v0
	v_max_f32_e32 v177, v177, v0
	v_cmp_ge_f32_e32 vcc, s90, v177
	s_cmp_eq_u64 vcc, exec
	s_cbranch_scc0 .Lmla_h5_newmax
; __device__ __forceinline__ void finishSM9(f32x16& p0, f32x16& p1, float alpha, float& l_reg, v8i32& p8) {
; #pragma unroll
;   for (int r = 0; r < 16; ++r) { p0[r] = __builtin_amdgcn_exp2f(p0[r]); p1[r] = __builtin_amdgcn_exp2f(p1[r]); }
;   float ps = 0;
; #pragma unroll
;   for (int r = 0; r < 16; ++r) ps += p0[r];
; #pragma unroll
;   for (int r = 0; r < 16; ++r) ps += p1[r];
;   { auto rr = __builtin_amdgcn_permlane32_swap(__float_as_uint(ps), __float_as_uint(ps), false, false);
;     ps = __uint_as_float(rr[0]) + __uint_as_float(rr[1]); }
;   l_reg = l_reg * alpha + ps;
; #pragma unroll
;   for (int g = 0; g < 4; ++g) {
;     int w = __builtin_amdgcn_cvt_pk_fp8_f32(p0[4 * g], p0[4 * g + 1], 0, false); p8[g] = __builtin_amdgcn_cvt_pk_fp8_f32(p0[4 * g + 2], p0[4 * g + 3], w, true);
;     int u = __builtin_amdgcn_cvt_pk_fp8_f32(p1[4 * g], p1[4 * g + 1], 0, false); p8[4 + g] = __builtin_amdgcn_cvt_pk_fp8_f32(p1[4 * g + 2], p1[4 * g + 3], u, true); }
; }
; __device__ __forceinline__ void pv8(f32x16* o, const char* Vt, const v8i32 p8, int r32, int hi) {
;   const int sw = (r32 >> 2) & 3, a0 = r32 * 64 + (((hi * 2) ^ sw) << 4), a1 = r32 * 64 + (((hi * 2 + 1) ^ sw) << 4);
; #pragma unroll
;   for (int d0 = 0; d0 < 4; ++d0) {
;     const v8i32 vf = cat8(*reinterpret_cast<const v4i32*>(Vt + d0 * 2048 + a0), *reinterpret_cast<const v4i32*>(Vt + d0 * 2048 + a1));
;     o[d0] = __builtin_amdgcn_mfma_scale_f32_32x32x64_f8f6f4(p8, vf, o[d0], 0, 0, 0, 127, 0, 127); }
; }
; __device__ __forceinline__ void qkt9(f32x16& p0, f32x16& p1, const char* Kn, const char* Kr, const v8i32* qf, const float init, int r32, int hi) {
; #pragma unroll
;   for (int r = 0; r < 16; ++r) { p0[r] = init; p1[r] = init; }
; #pragma unroll
;   for (int s = 0; s < 2; ++s) { const int c0 = s * 4 + hi * 2;
;     const v8i32 a0 = cat8(*reinterpret_cast<const v4i32*>(Kn + KN8SW(r32, c0)), *reinterpret_cast<const v4i32*>(Kn + KN8SW(r32, c0 + 1)));
;     const v8i32 a1 = cat8(*reinterpret_cast<const v4i32*>(Kn + 4096 + KN8SW(r32, c0)), *reinterpret_cast<const v4i32*>(Kn + 4096 + KN8SW(r32, c0 + 1)));
;     p0 = __builtin_amdgcn_mfma_scale_f32_32x32x64_f8f6f4(a0, qf[s], p0, 0, 0, 0, 127, 0, 124);
;     p1 = __builtin_amdgcn_mfma_scale_f32_32x32x64_f8f6f4(a1, qf[s], p1, 0, 0, 0, 127, 0, 124); }
;   { const int c0 = hi * 2;
.Lmla_h5_cont:
	s_add_i32 s30, s30, 1
	s_cmpk_lt_u32 s30, 42
	s_cbranch_scc1 .LBB0_1321
	ds_read_b128 v[114:117], v215 offset:24576
	ds_read_b128 v[118:121], v216 offset:24576
	ds_read_b128 v[222:225], v215 offset:28672
	ds_read_b128 v[226:229], v216 offset:28672
	v_exp_f32_e32 v0, v82
	v_exp_f32_e32 v177, v83
	v_exp_f32_e32 v179, v84
	v_exp_f32_e32 v254, v85
	v_add_f32_e32 v219, v0, v177
	v_cvt_pk_fp8_f32 v246, v0, v177
	v_add_f32_e32 v219, v179, v219
	v_add_f32_e32 v219, v254, v219
	v_cvt_pk_fp8_f32 v246, v179, v254 op_sel:[0,0,1]
	s_waitcnt lgkmcnt(2)
	v_mfma_scale_f32_32x32x64_f8f6f4 v[114:129], v[114:121], v[146:153], v[230:245], v194, v193 op_sel_hi:[0,0,0]
	global_load_dwordx4 v[158:161], v176, s[18:19]
	global_load_dwordx4 v[162:165], v178, s[16:17]
	global_load_dwordx4 v[154:157], v[180:181], off
	v_add_u32_e32 v176, 0x2000, v176
	v_add_u32_e32 v178, 0x20000, v178
	s_mov_b64 s[20:21], 0x1000
	v_lshl_add_u64 v[180:181], v[180:181], 0, s[20:21]
	v_exp_f32_e32 v0, v86
	v_exp_f32_e32 v177, v87
	v_exp_f32_e32 v179, v88
	v_exp_f32_e32 v254, v89
	v_add_f32_e32 v219, v0, v219
	v_add_f32_e32 v219, v177, v219
	v_cvt_pk_fp8_f32 v247, v0, v177
	v_add_f32_e32 v219, v179, v219
	v_add_f32_e32 v219, v254, v219
	v_cvt_pk_fp8_f32 v247, v179, v254 op_sel:[0,0,1]
	ds_read_b128 v[82:85], v213 offset:24576
	ds_read_b128 v[86:89], v214 offset:24576
	s_waitcnt lgkmcnt(2)
	v_mfma_scale_f32_32x32x64_f8f6f4 v[98:113], v[222:229], v[146:153], v[230:245], v194, v193 op_sel_hi:[0,0,0]
	ds_read_b128 v[222:225], v213 offset:28672
	ds_read_b128 v[226:229], v214 offset:28672
	v_exp_f32_e32 v0, v90
	v_exp_f32_e32 v177, v91
	v_exp_f32_e32 v179, v92
	v_exp_f32_e32 v254, v93
	v_add_f32_e32 v219, v0, v219
	v_add_f32_e32 v219, v177, v219
	v_cvt_pk_fp8_f32 v248, v0, v177
	v_add_f32_e32 v219, v179, v219
	v_add_f32_e32 v219, v254, v219
	v_cvt_pk_fp8_f32 v248, v179, v254 op_sel:[0,0,1]
	v_exp_f32_e32 v0, v94
	v_exp_f32_e32 v177, v95
	v_exp_f32_e32 v179, v96
	v_exp_f32_e32 v254, v97
	v_add_f32_e32 v219, v0, v219
	v_add_f32_e32 v219, v177, v219
	v_cvt_pk_fp8_f32 v249, v0, v177
	v_add_f32_e32 v219, v179, v219
	v_add_f32_e32 v219, v254, v219
	v_cvt_pk_fp8_f32 v249, v179, v254 op_sel:[0,0,1]
	ds_read_b128 v[90:93], v185 offset:36864
	ds_read_b128 v[94:97], v186 offset:36864
	s_waitcnt lgkmcnt(4)
	v_mfma_scale_f32_32x32x64_f8f6f4 v[114:129], v[82:89], v[138:145], v[114:129], v194, v193 op_sel_hi:[0,0,0]
	v_exp_f32_e32 v0, v66
	v_exp_f32_e32 v177, v67
	v_exp_f32_e32 v179, v68
	v_exp_f32_e32 v254, v69
	v_add_f32_e32 v219, v0, v219
	v_add_f32_e32 v219, v177, v219
	v_cvt_pk_fp8_f32 v250, v0, v177
	v_add_f32_e32 v219, v179, v219
	v_add_f32_e32 v219, v254, v219
	v_cvt_pk_fp8_f32 v250, v179, v254 op_sel:[0,0,1]
	s_waitcnt lgkmcnt(2)
	v_mfma_scale_f32_32x32x64_f8f6f4 v[98:113], v[222:229], v[138:145], v[98:113], v194, v193 op_sel_hi:[0,0,0]
	ds_read_b128 v[222:225], v185 offset:38912
	ds_read_b128 v[226:229], v186 offset:38912
	v_exp_f32_e32 v0, v70
	v_exp_f32_e32 v177, v71
	v_exp_f32_e32 v179, v72
	v_exp_f32_e32 v254, v73
	v_add_f32_e32 v219, v0, v219
	v_add_f32_e32 v219, v177, v219
	v_cvt_pk_fp8_f32 v251, v0, v177
	v_add_f32_e32 v219, v179, v219
	v_add_f32_e32 v219, v254, v219
	v_cvt_pk_fp8_f32 v251, v179, v254 op_sel:[0,0,1]
	v_exp_f32_e32 v0, v74
	v_exp_f32_e32 v177, v75
	v_exp_f32_e32 v179, v76
	v_exp_f32_e32 v254, v77
	v_add_f32_e32 v219, v0, v219
	v_add_f32_e32 v219, v177, v219
	v_cvt_pk_fp8_f32 v252, v0, v177
	v_add_f32_e32 v219, v179, v219
	v_add_f32_e32 v219, v254, v219
	v_cvt_pk_fp8_f32 v252, v179, v254 op_sel:[0,0,1]
	s_waitcnt lgkmcnt(2)
	v_mfma_scale_f32_32x32x64_f8f6f4 v[114:129], v[90:97], v[130:137], v[114:129], v194, v193 op_sel_hi:[0,0,0]
	v_exp_f32_e32 v0, v78
	v_exp_f32_e32 v177, v79
	v_exp_f32_e32 v179, v80
	v_exp_f32_e32 v254, v81
	v_add_f32_e32 v219, v0, v219
	v_add_f32_e32 v219, v177, v219
	v_cvt_pk_fp8_f32 v253, v0, v177
	v_add_f32_e32 v219, v179, v219
	v_add_f32_e32 v219, v254, v219
	v_cvt_pk_fp8_f32 v253, v179, v254 op_sel:[0,0,1]
	ds_read_b128 v[90:93], v185 offset:0
	ds_read_b128 v[94:97], v186 offset:0
	ds_read_b128 v[82:85], v185 offset:2048
	ds_read_b128 v[86:89], v186 offset:2048
	ds_read_b128 v[74:77], v185 offset:4096
	ds_read_b128 v[78:81], v186 offset:4096
	ds_read_b128 v[66:69], v185 offset:6144
	ds_read_b128 v[70:73], v186 offset:6144
	s_waitcnt lgkmcnt(8)
	v_mfma_scale_f32_32x32x64_f8f6f4 v[98:113], v[222:229], v[130:137], v[98:113], v194, v193 op_sel_hi:[0,0,0]
	v_mov_b32_e32 v0, v219
	s_nop 1
	v_permlane32_swap_b32_e32 v219, v0
	v_add_f32_e32 v219, v219, v0
	v_fma_f32 v209, v209, v218, v219
	v_max_f32_e32 v177, v114, v115
	v_max3_f32 v177, v177, v116, v117
	v_max3_f32 v177, v177, v118, v119
	v_max3_f32 v177, v177, v120, v121
	v_max3_f32 v177, v177, v122, v123
	v_max3_f32 v177, v177, v124, v125
	v_max3_f32 v177, v177, v126, v127
	v_max3_f32 v177, v177, v128, v129
	s_waitcnt lgkmcnt(6)
	v_mfma_scale_f32_32x32x64_f8f6f4 v[50:65], v[246:253], v[90:97], v[50:65], v194, v194 op_sel_hi:[0,0,0]
	s_waitcnt lgkmcnt(4)
	v_mfma_scale_f32_32x32x64_f8f6f4 v[34:49], v[246:253], v[82:89], v[34:49], v194, v194 op_sel_hi:[0,0,0]
	s_waitcnt lgkmcnt(2)
	v_mfma_scale_f32_32x32x64_f8f6f4 v[18:33], v[246:253], v[74:81], v[18:33], v194, v194 op_sel_hi:[0,0,0]
	s_waitcnt vmcnt(0)
	ds_write_b128 v210, v[158:161] offset:43008
	ds_write_b128 v211, v[162:165] offset:51200
	ds_write_b128 v212, v[154:157] offset:59392
	s_waitcnt lgkmcnt(3)
	v_mfma_scale_f32_32x32x64_f8f6f4 v[2:17], v[246:253], v[66:73], v[2:17], v194, v194 op_sel_hi:[0,0,0]
	s_waitcnt lgkmcnt(0)
	s_barrier
	v_max_f32_e32 v0, v98, v99
	v_max3_f32 v0, v0, v100, v101
	v_max3_f32 v0, v0, v102, v103
	v_max3_f32 v0, v0, v104, v105
	v_max3_f32 v0, v0, v106, v107
	v_max3_f32 v0, v0, v108, v109
	v_max3_f32 v0, v0, v110, v111
	v_max3_f32 v0, v0, v112, v113
	v_max_f32_e32 v177, v177, v0
	v_mov_b32_e32 v0, v177
	v_mov_b32_e32 v221, 1.0
	s_nop 0
	v_permlane32_swap_b32_e32 v177, v0
	v_max_f32_e32 v177, v177, v0
	v_cmp_ge_f32_e32 vcc, s90, v177
	s_cmp_eq_u64 vcc, exec
	s_cbranch_scc0 .Lmla_p0_newmax

; __device__ __forceinline__ void finishSM9(f32x16& p0, f32x16& p1, float alpha, float& l_reg, v8i32& p8) {
; #pragma unroll
;   for (int r = 0; r < 16; ++r) { p0[r] = __builtin_amdgcn_exp2f(p0[r]); p1[r] = __builtin_amdgcn_exp2f(p1[r]); }
;   float ps = 0;
; #pragma unroll
;   for (int r = 0; r < 16; ++r) ps += p0[r];
; #pragma unroll
;   for (int r = 0; r < 16; ++r) ps += p1[r];
;   { auto rr = __builtin_amdgcn_permlane32_swap(__float_as_uint(ps), __float_as_uint(ps), false, false);
;     ps = __uint_as_float(rr[0]) + __uint_as_float(rr[1]); }
;   l_reg = l_reg * alpha + ps;
; #pragma unroll
;   for (int g = 0; g < 4; ++g) {
;     int w = __builtin_amdgcn_cvt_pk_fp8_f32(p0[4 * g], p0[4 * g + 1], 0, false); p8[g] = __builtin_amdgcn_cvt_pk_fp8_f32(p0[4 * g + 2], p0[4 * g + 3], w, true);
;     int u = __builtin_amdgcn_cvt_pk_fp8_f32(p1[4 * g], p1[4 * g + 1], 0, false); p8[4 + g] = __builtin_amdgcn_cvt_pk_fp8_f32(p1[4 * g + 2], p1[4 * g + 3], u, true); }
; }
; __device__ __forceinline__ void pv8(f32x16* o, const char* Vt, const v8i32 p8, int r32, int hi) {
;   const int sw = (r32 >> 2) & 3, a0 = r32 * 64 + (((hi * 2) ^ sw) << 4), a1 = r32 * 64 + (((hi * 2 + 1) ^ sw) << 4);
; #pragma unroll
;   for (int d0 = 0; d0 < 4; ++d0) {
;     const v8i32 vf = cat8(*reinterpret_cast<const v4i32*>(Vt + d0 * 2048 + a0), *reinterpret_cast<const v4i32*>(Vt + d0 * 2048 + a1));
;     o[d0] = __builtin_amdgcn_mfma_scale_f32_32x32x64_f8f6f4(p8, vf, o[d0], 0, 0, 0, 127, 0, 127); }
; }
; __device__ __forceinline__ void qkt9(f32x16& p0, f32x16& p1, const char* Kn, const char* Kr, const v8i32* qf, const float init, int r32, int hi) {
; #pragma unroll
;   for (int r = 0; r < 16; ++r) { p0[r] = init; p1[r] = init; }
; #pragma unroll
;   for (int s = 0; s < 2; ++s) { const int c0 = s * 4 + hi * 2;
;     const v8i32 a0 = cat8(*reinterpret_cast<const v4i32*>(Kn + KN8SW(r32, c0)), *reinterpret_cast<const v4i32*>(Kn + KN8SW(r32, c0 + 1)));
;     const v8i32 a1 = cat8(*reinterpret_cast<const v4i32*>(Kn + 4096 + KN8SW(r32, c0)), *reinterpret_cast<const v4i32*>(Kn + 4096 + KN8SW(r32, c0 + 1)));
;     p0 = __builtin_amdgcn_mfma_scale_f32_32x32x64_f8f6f4(a0, qf[s], p0, 0, 0, 0, 127, 0, 124);
;     p1 = __builtin_amdgcn_mfma_scale_f32_32x32x64_f8f6f4(a1, qf[s], p1, 0, 0, 0, 127, 0, 124); }
;   { const int c0 = hi * 2;
.Lmla_stag_loop:
	ds_read_b128 v[114:117], v215 offset:24576
	ds_read_b128 v[118:121], v216 offset:24576
	ds_read_b128 v[222:225], v215 offset:28672
	ds_read_b128 v[226:229], v216 offset:28672
	v_exp_f32_e32 v0, v82
	v_exp_f32_e32 v177, v83
	v_exp_f32_e32 v179, v84
	v_exp_f32_e32 v254, v85
	v_add_f32_e32 v219, v0, v177
	v_cvt_pk_fp8_f32 v246, v0, v177
	v_add_f32_e32 v219, v179, v219
	v_add_f32_e32 v219, v254, v219
	v_cvt_pk_fp8_f32 v246, v179, v254 op_sel:[0,0,1]
	s_waitcnt lgkmcnt(2)
	v_mfma_scale_f32_32x32x64_f8f6f4 v[114:129], v[114:121], v[146:153], v[230:245], v194, v193 op_sel_hi:[0,0,0]
	v_exp_f32_e32 v0, v86
	v_exp_f32_e32 v177, v87
	v_exp_f32_e32 v179, v88
	v_exp_f32_e32 v254, v89
	v_add_f32_e32 v219, v0, v219
	v_add_f32_e32 v219, v177, v219
	v_cvt_pk_fp8_f32 v247, v0, v177
	v_add_f32_e32 v219, v179, v219
	v_add_f32_e32 v219, v254, v219
	v_cvt_pk_fp8_f32 v247, v179, v254 op_sel:[0,0,1]
	ds_read_b128 v[82:85], v213 offset:24576
	ds_read_b128 v[86:89], v214 offset:24576
	s_waitcnt lgkmcnt(2)
	v_mfma_scale_f32_32x32x64_f8f6f4 v[98:113], v[222:229], v[146:153], v[230:245], v194, v193 op_sel_hi:[0,0,0]
	ds_read_b128 v[222:225], v213 offset:28672
	ds_read_b128 v[226:229], v214 offset:28672
	v_exp_f32_e32 v0, v90
	v_exp_f32_e32 v177, v91
	v_exp_f32_e32 v179, v92
	v_exp_f32_e32 v254, v93
	v_add_f32_e32 v219, v0, v219
	v_add_f32_e32 v219, v177, v219
	v_cvt_pk_fp8_f32 v248, v0, v177
	v_add_f32_e32 v219, v179, v219
	v_add_f32_e32 v219, v254, v219
	v_cvt_pk_fp8_f32 v248, v179, v254 op_sel:[0,0,1]
	v_exp_f32_e32 v0, v94
	v_exp_f32_e32 v177, v95
	v_exp_f32_e32 v179, v96
	v_exp_f32_e32 v254, v97
	v_add_f32_e32 v219, v0, v219
	v_add_f32_e32 v219, v177, v219
	v_cvt_pk_fp8_f32 v249, v0, v177
	v_add_f32_e32 v219, v179, v219
	v_add_f32_e32 v219, v254, v219
	v_cvt_pk_fp8_f32 v249, v179, v254 op_sel:[0,0,1]
	ds_read_b128 v[90:93], v185 offset:36864
	ds_read_b128 v[94:97], v186 offset:36864
	s_waitcnt lgkmcnt(4)
	v_mfma_scale_f32_32x32x64_f8f6f4 v[114:129], v[82:89], v[138:145], v[114:129], v194, v193 op_sel_hi:[0,0,0]
	v_exp_f32_e32 v0, v66
	v_exp_f32_e32 v177, v67
	v_exp_f32_e32 v179, v68
	v_exp_f32_e32 v254, v69
	v_add_f32_e32 v219, v0, v219
	v_add_f32_e32 v219, v177, v219
	v_cvt_pk_fp8_f32 v250, v0, v177
	v_add_f32_e32 v219, v179, v219
	v_add_f32_e32 v219, v254, v219
	v_cvt_pk_fp8_f32 v250, v179, v254 op_sel:[0,0,1]
	s_waitcnt lgkmcnt(2)
	v_mfma_scale_f32_32x32x64_f8f6f4 v[98:113], v[222:229], v[138:145], v[98:113], v194, v193 op_sel_hi:[0,0,0]
	ds_read_b128 v[222:225], v185 offset:38912
	ds_read_b128 v[226:229], v186 offset:38912
	v_exp_f32_e32 v0, v70
	v_exp_f32_e32 v177, v71
	v_exp_f32_e32 v179, v72
	v_exp_f32_e32 v254, v73
	v_add_f32_e32 v219, v0, v219
	v_add_f32_e32 v219, v177, v219
	v_cvt_pk_fp8_f32 v251, v0, v177
	v_add_f32_e32 v219, v179, v219
	v_add_f32_e32 v219, v254, v219
	v_cvt_pk_fp8_f32 v251, v179, v254 op_sel:[0,0,1]
	v_exp_f32_e32 v0, v74
	v_exp_f32_e32 v177, v75
	v_exp_f32_e32 v179, v76
	v_exp_f32_e32 v254, v77
	v_add_f32_e32 v219, v0, v219
	v_add_f32_e32 v219, v177, v219
	v_cvt_pk_fp8_f32 v252, v0, v177
	v_add_f32_e32 v219, v179, v219
	v_add_f32_e32 v219, v254, v219
	v_cvt_pk_fp8_f32 v252, v179, v254 op_sel:[0,0,1]
	s_waitcnt lgkmcnt(2)
	v_mfma_scale_f32_32x32x64_f8f6f4 v[114:129], v[90:97], v[130:137], v[114:129], v194, v193 op_sel_hi:[0,0,0]
	v_exp_f32_e32 v0, v78
	v_exp_f32_e32 v177, v79
	v_exp_f32_e32 v179, v80
	v_exp_f32_e32 v254, v81
	v_add_f32_e32 v219, v0, v219
	v_add_f32_e32 v219, v177, v219
	v_cvt_pk_fp8_f32 v253, v0, v177
	v_add_f32_e32 v219, v179, v219
	v_add_f32_e32 v219, v254, v219
	v_cvt_pk_fp8_f32 v253, v179, v254 op_sel:[0,0,1]
	ds_read_b128 v[90:93], v185 offset:0
	ds_read_b128 v[94:97], v186 offset:0
	ds_read_b128 v[82:85], v185 offset:2048
	ds_read_b128 v[86:89], v186 offset:2048
	ds_read_b128 v[74:77], v185 offset:4096
	ds_read_b128 v[78:81], v186 offset:4096
	ds_read_b128 v[66:69], v185 offset:6144
	ds_read_b128 v[70:73], v186 offset:6144
	s_waitcnt lgkmcnt(8)
	v_mfma_scale_f32_32x32x64_f8f6f4 v[98:113], v[222:229], v[130:137], v[98:113], v194, v193 op_sel_hi:[0,0,0]
	v_mov_b32_e32 v0, v219
	s_nop 1
	v_permlane32_swap_b32_e32 v219, v0
	v_add_f32_e32 v219, v219, v0
	v_fma_f32 v209, v209, v218, v219
	v_max_f32_e32 v177, v114, v115
	v_max3_f32 v177, v177, v116, v117
	v_max3_f32 v177, v177, v118, v119
	v_max3_f32 v177, v177, v120, v121
	v_max3_f32 v177, v177, v122, v123
	v_max3_f32 v177, v177, v124, v125
	v_max3_f32 v177, v177, v126, v127
	v_max3_f32 v177, v177, v128, v129
	s_waitcnt lgkmcnt(6)
	v_mfma_scale_f32_32x32x64_f8f6f4 v[50:65], v[246:253], v[90:97], v[50:65], v194, v194 op_sel_hi:[0,0,0]
	s_waitcnt vmcnt(0)
	ds_write_b128 v210, v[158:161] offset:43008
	ds_write_b128 v211, v[162:165] offset:51200
	s_waitcnt lgkmcnt(6)
	v_mfma_scale_f32_32x32x64_f8f6f4 v[34:49], v[246:253], v[82:89], v[34:49], v194, v194 op_sel_hi:[0,0,0]
	s_waitcnt lgkmcnt(0)
	s_barrier
	s_waitcnt lgkmcnt(2)
	v_mfma_scale_f32_32x32x64_f8f6f4 v[18:33], v[246:253], v[74:81], v[18:33], v194, v194 op_sel_hi:[0,0,0]
	s_waitcnt lgkmcnt(0)
	v_mfma_scale_f32_32x32x64_f8f6f4 v[2:17], v[246:253], v[66:73], v[2:17], v194, v194 op_sel_hi:[0,0,0]
	global_load_dwordx4 v[158:161], v176, s[18:19]
	global_load_dwordx4 v[162:165], v178, s[16:17]
	v_add_u32_e32 v176, 0x2000, v176
	v_add_u32_e32 v178, 0x20000, v178
	v_max_f32_e32 v0, v98, v99
	v_max3_f32 v0, v0, v100, v101
	v_max3_f32 v0, v0, v102, v103
	v_max3_f32 v0, v0, v104, v105
	v_max3_f32 v0, v0, v106, v107
	v_max3_f32 v0, v0, v108, v109
	v_max3_f32 v0, v0, v110, v111
	v_max3_f32 v0, v0, v112, v113
	v_max_f32_e32 v177, v177, v0
	v_mov_b32_e32 v0, v177
	v_mov_b32_e32 v221, 1.0
	s_nop 0
	v_permlane32_swap_b32_e32 v177, v0
	v_max_f32_e32 v177, v177, v0
	v_cmp_ge_f32_e32 vcc, s90, v177
	s_cmp_eq_u64 vcc, exec
	s_cbranch_scc0 .Lmla_s0_newmax
; __device__ __forceinline__ void finishSM9(f32x16& p0, f32x16& p1, float alpha, float& l_reg, v8i32& p8) {
; #pragma unroll
;   for (int r = 0; r < 16; ++r) { p0[r] = __builtin_amdgcn_exp2f(p0[r]); p1[r] = __builtin_amdgcn_exp2f(p1[r]); }
;   float ps = 0;
; #pragma unroll
;   for (int r = 0; r < 16; ++r) ps += p0[r];
; #pragma unroll
;   for (int r = 0; r < 16; ++r) ps += p1[r];
;   { auto rr = __builtin_amdgcn_permlane32_swap(__float_as_uint(ps), __float_as_uint(ps), false, false);
;     ps = __uint_as_float(rr[0]) + __uint_as_float(rr[1]); }
;   l_reg = l_reg * alpha + ps;
; #pragma unroll
;   for (int g = 0; g < 4; ++g) {
;     int w = __builtin_amdgcn_cvt_pk_fp8_f32(p0[4 * g], p0[4 * g + 1], 0, false); p8[g] = __builtin_amdgcn_cvt_pk_fp8_f32(p0[4 * g + 2], p0[4 * g + 3], w, true);
;     int u = __builtin_amdgcn_cvt_pk_fp8_f32(p1[4 * g], p1[4 * g + 1], 0, false); p8[4 + g] = __builtin_amdgcn_cvt_pk_fp8_f32(p1[4 * g + 2], p1[4 * g + 3], u, true); }
; }
; __device__ __forceinline__ void pv8(f32x16* o, const char* Vt, const v8i32 p8, int r32, int hi) {
;   const int sw = (r32 >> 2) & 3, a0 = r32 * 64 + (((hi * 2) ^ sw) << 4), a1 = r32 * 64 + (((hi * 2 + 1) ^ sw) << 4);
; #pragma unroll
;   for (int d0 = 0; d0 < 4; ++d0) {
;     const v8i32 vf = cat8(*reinterpret_cast<const v4i32*>(Vt + d0 * 2048 + a0), *reinterpret_cast<const v4i32*>(Vt + d0 * 2048 + a1));
;     o[d0] = __builtin_amdgcn_mfma_scale_f32_32x32x64_f8f6f4(p8, vf, o[d0], 0, 0, 0, 127, 0, 127); }
; }
; __device__ __forceinline__ void qkt9(f32x16& p0, f32x16& p1, const char* Kn, const char* Kr, const v8i32* qf, const float init, int r32, int hi) {
; #pragma unroll
;   for (int r = 0; r < 16; ++r) { p0[r] = init; p1[r] = init; }
; #pragma unroll
;   for (int s = 0; s < 2; ++s) { const int c0 = s * 4 + hi * 2;
;     const v8i32 a0 = cat8(*reinterpret_cast<const v4i32*>(Kn + KN8SW(r32, c0)), *reinterpret_cast<const v4i32*>(Kn + KN8SW(r32, c0 + 1)));
;     const v8i32 a1 = cat8(*reinterpret_cast<const v4i32*>(Kn + 4096 + KN8SW(r32, c0)), *reinterpret_cast<const v4i32*>(Kn + 4096 + KN8SW(r32, c0 + 1)));
;     p0 = __builtin_amdgcn_mfma_scale_f32_32x32x64_f8f6f4(a0, qf[s], p0, 0, 0, 0, 127, 0, 124);
;     p1 = __builtin_amdgcn_mfma_scale_f32_32x32x64_f8f6f4(a1, qf[s], p1, 0, 0, 0, 127, 0, 124); }
;   { const int c0 = hi * 2;
.Lmla_s0_cont:
	ds_read_b128 v[82:85], v215 offset:51200
	ds_read_b128 v[86:89], v216 offset:51200
	ds_read_b128 v[222:225], v215 offset:55296
	ds_read_b128 v[226:229], v216 offset:55296
	v_exp_f32_e32 v0, v114
	v_exp_f32_e32 v177, v115
	v_exp_f32_e32 v179, v116
	v_exp_f32_e32 v254, v117
	v_add_f32_e32 v219, v0, v177
	v_cvt_pk_fp8_f32 v246, v0, v177
	v_add_f32_e32 v219, v179, v219
	v_add_f32_e32 v219, v254, v219
	v_cvt_pk_fp8_f32 v246, v179, v254 op_sel:[0,0,1]
	s_waitcnt lgkmcnt(2)
	v_mfma_scale_f32_32x32x64_f8f6f4 v[82:97], v[82:89], v[146:153], v[230:245], v194, v193 op_sel_hi:[0,0,0]
	v_exp_f32_e32 v0, v118
	v_exp_f32_e32 v177, v119
	v_exp_f32_e32 v179, v120
	v_exp_f32_e32 v254, v121
	v_add_f32_e32 v219, v0, v219
	v_add_f32_e32 v219, v177, v219
	v_cvt_pk_fp8_f32 v247, v0, v177
	v_add_f32_e32 v219, v179, v219
	v_add_f32_e32 v219, v254, v219
	v_cvt_pk_fp8_f32 v247, v179, v254 op_sel:[0,0,1]
	ds_read_b128 v[114:117], v213 offset:51200
	ds_read_b128 v[118:121], v214 offset:51200
	s_waitcnt lgkmcnt(2)
	v_mfma_scale_f32_32x32x64_f8f6f4 v[66:81], v[222:229], v[146:153], v[230:245], v194, v193 op_sel_hi:[0,0,0]
	ds_read_b128 v[222:225], v213 offset:55296
	ds_read_b128 v[226:229], v214 offset:55296
	v_exp_f32_e32 v0, v122
	v_exp_f32_e32 v177, v123
	v_exp_f32_e32 v179, v124
	v_exp_f32_e32 v254, v125
	v_add_f32_e32 v219, v0, v219
	v_add_f32_e32 v219, v177, v219
	v_cvt_pk_fp8_f32 v248, v0, v177
	v_add_f32_e32 v219, v179, v219
	v_add_f32_e32 v219, v254, v219
	v_cvt_pk_fp8_f32 v248, v179, v254 op_sel:[0,0,1]
	v_exp_f32_e32 v0, v126
	v_exp_f32_e32 v177, v127
	v_exp_f32_e32 v179, v128
	v_exp_f32_e32 v254, v129
	v_add_f32_e32 v219, v0, v219
	v_add_f32_e32 v219, v177, v219
	v_cvt_pk_fp8_f32 v249, v0, v177
	v_add_f32_e32 v219, v179, v219
	v_add_f32_e32 v219, v254, v219
	v_cvt_pk_fp8_f32 v249, v179, v254 op_sel:[0,0,1]
	ds_read_b128 v[122:125], v185 offset:59392
	ds_read_b128 v[126:129], v186 offset:59392
	s_waitcnt lgkmcnt(4)
	v_mfma_scale_f32_32x32x64_f8f6f4 v[82:97], v[114:121], v[138:145], v[82:97], v194, v193 op_sel_hi:[0,0,0]
	v_exp_f32_e32 v0, v98
	v_exp_f32_e32 v177, v99
	v_exp_f32_e32 v179, v100
	v_exp_f32_e32 v254, v101
	v_add_f32_e32 v219, v0, v219
	v_add_f32_e32 v219, v177, v219
	v_cvt_pk_fp8_f32 v250, v0, v177
	v_add_f32_e32 v219, v179, v219
	v_add_f32_e32 v219, v254, v219
	v_cvt_pk_fp8_f32 v250, v179, v254 op_sel:[0,0,1]
	s_waitcnt lgkmcnt(2)
	v_mfma_scale_f32_32x32x64_f8f6f4 v[66:81], v[222:229], v[138:145], v[66:81], v194, v193 op_sel_hi:[0,0,0]
	ds_read_b128 v[222:225], v185 offset:61440
	ds_read_b128 v[226:229], v186 offset:61440
	v_exp_f32_e32 v0, v102
	v_exp_f32_e32 v177, v103
	v_exp_f32_e32 v179, v104
	v_exp_f32_e32 v254, v105
	v_add_f32_e32 v219, v0, v219
	v_add_f32_e32 v219, v177, v219
	v_cvt_pk_fp8_f32 v251, v0, v177
	v_add_f32_e32 v219, v179, v219
	v_add_f32_e32 v219, v254, v219
	v_cvt_pk_fp8_f32 v251, v179, v254 op_sel:[0,0,1]
	v_exp_f32_e32 v0, v106
	v_exp_f32_e32 v177, v107
	v_exp_f32_e32 v179, v108
	v_exp_f32_e32 v254, v109
	v_add_f32_e32 v219, v0, v219
	v_add_f32_e32 v219, v177, v219
	v_cvt_pk_fp8_f32 v252, v0, v177
	v_add_f32_e32 v219, v179, v219
	v_add_f32_e32 v219, v254, v219
	v_cvt_pk_fp8_f32 v252, v179, v254 op_sel:[0,0,1]
	s_waitcnt lgkmcnt(2)
	v_mfma_scale_f32_32x32x64_f8f6f4 v[82:97], v[122:129], v[130:137], v[82:97], v194, v193 op_sel_hi:[0,0,0]
	v_exp_f32_e32 v0, v110
	v_exp_f32_e32 v177, v111
	v_exp_f32_e32 v179, v112
	v_exp_f32_e32 v254, v113
	v_add_f32_e32 v219, v0, v219
	v_add_f32_e32 v219, v177, v219
	v_cvt_pk_fp8_f32 v253, v0, v177
	v_add_f32_e32 v219, v179, v219
	v_add_f32_e32 v219, v254, v219
	v_cvt_pk_fp8_f32 v253, v179, v254 op_sel:[0,0,1]
	ds_read_b128 v[122:125], v185 offset:8192
	ds_read_b128 v[126:129], v186 offset:8192
	ds_read_b128 v[114:117], v185 offset:10240
	ds_read_b128 v[118:121], v186 offset:10240
	ds_read_b128 v[106:109], v185 offset:12288
	ds_read_b128 v[110:113], v186 offset:12288
	ds_read_b128 v[98:101], v185 offset:14336
	ds_read_b128 v[102:105], v186 offset:14336
	s_waitcnt lgkmcnt(8)
	v_mfma_scale_f32_32x32x64_f8f6f4 v[66:81], v[222:229], v[130:137], v[66:81], v194, v193 op_sel_hi:[0,0,0]
	v_mov_b32_e32 v0, v219
	s_nop 1
	v_permlane32_swap_b32_e32 v219, v0
	v_add_f32_e32 v219, v219, v0
	v_fma_f32 v209, v209, v221, v219
	v_max_f32_e32 v177, v82, v83
	v_max3_f32 v177, v177, v84, v85
	v_max3_f32 v177, v177, v86, v87
	v_max3_f32 v177, v177, v88, v89
	v_max3_f32 v177, v177, v90, v91
	v_max3_f32 v177, v177, v92, v93
	v_max3_f32 v177, v177, v94, v95
	v_max3_f32 v177, v177, v96, v97
	s_waitcnt lgkmcnt(6)
	v_mfma_scale_f32_32x32x64_f8f6f4 v[50:65], v[246:253], v[122:129], v[50:65], v194, v194 op_sel_hi:[0,0,0]
	s_waitcnt vmcnt(0)
	ds_write_b128 v210, v[158:161]
	ds_write_b128 v211, v[162:165] offset:16384
	s_waitcnt lgkmcnt(6)
	v_mfma_scale_f32_32x32x64_f8f6f4 v[34:49], v[246:253], v[114:121], v[34:49], v194, v194 op_sel_hi:[0,0,0]
	s_waitcnt lgkmcnt(0)
	s_barrier
	s_waitcnt lgkmcnt(2)
	v_mfma_scale_f32_32x32x64_f8f6f4 v[18:33], v[246:253], v[106:113], v[18:33], v194, v194 op_sel_hi:[0,0,0]
	s_waitcnt lgkmcnt(0)
	v_mfma_scale_f32_32x32x64_f8f6f4 v[2:17], v[246:253], v[98:105], v[2:17], v194, v194 op_sel_hi:[0,0,0]
	global_load_dwordx4 v[158:161], v176, s[18:19]
	global_load_dwordx4 v[162:165], v178, s[16:17]
	v_add_u32_e32 v176, 0x2000, v176
	v_add_u32_e32 v178, 0x20000, v178
	v_max_f32_e32 v0, v66, v67
	v_max3_f32 v0, v0, v68, v69
	v_max3_f32 v0, v0, v70, v71
	v_max3_f32 v0, v0, v72, v73
	v_max3_f32 v0, v0, v74, v75
	v_max3_f32 v0, v0, v76, v77
	v_max3_f32 v0, v0, v78, v79
	v_max3_f32 v0, v0, v80, v81
	v_max_f32_e32 v177, v177, v0
	v_mov_b32_e32 v0, v177
	v_mov_b32_e32 v218, 1.0
	s_nop 0
	v_permlane32_swap_b32_e32 v177, v0
	v_max_f32_e32 v177, v177, v0
	v_cmp_ge_f32_e32 vcc, s90, v177
	s_cmp_eq_u64 vcc, exec
	s_cbranch_scc0 .Lmla_s1_newmax
; __device__ __forceinline__ void finishSM9(f32x16& p0, f32x16& p1, float alpha, float& l_reg, v8i32& p8) {
; #pragma unroll
;   for (int r = 0; r < 16; ++r) { p0[r] = __builtin_amdgcn_exp2f(p0[r]); p1[r] = __builtin_amdgcn_exp2f(p1[r]); }
;   float ps = 0;
; #pragma unroll
;   for (int r = 0; r < 16; ++r) ps += p0[r];
; #pragma unroll
;   for (int r = 0; r < 16; ++r) ps += p1[r];
;   { auto rr = __builtin_amdgcn_permlane32_swap(__float_as_uint(ps), __float_as_uint(ps), false, false);
;     ps = __uint_as_float(rr[0]) + __uint_as_float(rr[1]); }
;   l_reg = l_reg * alpha + ps;
; #pragma unroll
;   for (int g = 0; g < 4; ++g) {
;     int w = __builtin_amdgcn_cvt_pk_fp8_f32(p0[4 * g], p0[4 * g + 1], 0, false); p8[g] = __builtin_amdgcn_cvt_pk_fp8_f32(p0[4 * g + 2], p0[4 * g + 3], w, true);
;     int u = __builtin_amdgcn_cvt_pk_fp8_f32(p1[4 * g], p1[4 * g + 1], 0, false); p8[4 + g] = __builtin_amdgcn_cvt_pk_fp8_f32(p1[4 * g + 2], p1[4 * g + 3], u, true); }
; }
; __device__ __forceinline__ void pv8(f32x16* o, const char* Vt, const v8i32 p8, int r32, int hi) {
;   const int sw = (r32 >> 2) & 3, a0 = r32 * 64 + (((hi * 2) ^ sw) << 4), a1 = r32 * 64 + (((hi * 2 + 1) ^ sw) << 4);
; #pragma unroll
;   for (int d0 = 0; d0 < 4; ++d0) {
;     const v8i32 vf = cat8(*reinterpret_cast<const v4i32*>(Vt + d0 * 2048 + a0), *reinterpret_cast<const v4i32*>(Vt + d0 * 2048 + a1));
;     o[d0] = __builtin_amdgcn_mfma_scale_f32_32x32x64_f8f6f4(p8, vf, o[d0], 0, 0, 0, 127, 0, 127); }
; }
; __device__ __forceinline__ void qkt9(f32x16& p0, f32x16& p1, const char* Kn, const char* Kr, const v8i32* qf, const float init, int r32, int hi) {
; #pragma unroll
;   for (int r = 0; r < 16; ++r) { p0[r] = init; p1[r] = init; }
; #pragma unroll
;   for (int s = 0; s < 2; ++s) { const int c0 = s * 4 + hi * 2;
;     const v8i32 a0 = cat8(*reinterpret_cast<const v4i32*>(Kn + KN8SW(r32, c0)), *reinterpret_cast<const v4i32*>(Kn + KN8SW(r32, c0 + 1)));
;     const v8i32 a1 = cat8(*reinterpret_cast<const v4i32*>(Kn + 4096 + KN8SW(r32, c0)), *reinterpret_cast<const v4i32*>(Kn + 4096 + KN8SW(r32, c0 + 1)));
;     p0 = __builtin_amdgcn_mfma_scale_f32_32x32x64_f8f6f4(a0, qf[s], p0, 0, 0, 0, 127, 0, 124);
;     p1 = __builtin_amdgcn_mfma_scale_f32_32x32x64_f8f6f4(a1, qf[s], p1, 0, 0, 0, 127, 0, 124); }
;   { const int c0 = hi * 2;
.Lmla_s1_cont:
	ds_read_b128 v[114:117], v215 offset:16384
	ds_read_b128 v[118:121], v216 offset:16384
	ds_read_b128 v[222:225], v215 offset:20480
	ds_read_b128 v[226:229], v216 offset:20480
	v_exp_f32_e32 v0, v82
	v_exp_f32_e32 v177, v83
	v_exp_f32_e32 v179, v84
	v_exp_f32_e32 v254, v85
	v_add_f32_e32 v219, v0, v177
	v_cvt_pk_fp8_f32 v246, v0, v177
	v_add_f32_e32 v219, v179, v219
	v_add_f32_e32 v219, v254, v219
	v_cvt_pk_fp8_f32 v246, v179, v254 op_sel:[0,0,1]
	s_waitcnt lgkmcnt(2)
	v_mfma_scale_f32_32x32x64_f8f6f4 v[114:129], v[114:121], v[146:153], v[230:245], v194, v193 op_sel_hi:[0,0,0]
	v_exp_f32_e32 v0, v86
	v_exp_f32_e32 v177, v87
	v_exp_f32_e32 v179, v88
	v_exp_f32_e32 v254, v89
	v_add_f32_e32 v219, v0, v219
	v_add_f32_e32 v219, v177, v219
	v_cvt_pk_fp8_f32 v247, v0, v177
	v_add_f32_e32 v219, v179, v219
	v_add_f32_e32 v219, v254, v219
	v_cvt_pk_fp8_f32 v247, v179, v254 op_sel:[0,0,1]
	ds_read_b128 v[82:85], v213 offset:16384
	ds_read_b128 v[86:89], v214 offset:16384
	s_waitcnt lgkmcnt(2)
	v_mfma_scale_f32_32x32x64_f8f6f4 v[98:113], v[222:229], v[146:153], v[230:245], v194, v193 op_sel_hi:[0,0,0]
	ds_read_b128 v[222:225], v213 offset:20480
	ds_read_b128 v[226:229], v214 offset:20480
	v_exp_f32_e32 v0, v90
	v_exp_f32_e32 v177, v91
	v_exp_f32_e32 v179, v92
	v_exp_f32_e32 v254, v93
	v_add_f32_e32 v219, v0, v219
	v_add_f32_e32 v219, v177, v219
	v_cvt_pk_fp8_f32 v248, v0, v177
	v_add_f32_e32 v219, v179, v219
	v_add_f32_e32 v219, v254, v219
	v_cvt_pk_fp8_f32 v248, v179, v254 op_sel:[0,0,1]
	v_exp_f32_e32 v0, v94
	v_exp_f32_e32 v177, v95
	v_exp_f32_e32 v179, v96
	v_exp_f32_e32 v254, v97
	v_add_f32_e32 v219, v0, v219
	v_add_f32_e32 v219, v177, v219
	v_cvt_pk_fp8_f32 v249, v0, v177
	v_add_f32_e32 v219, v179, v219
	v_add_f32_e32 v219, v254, v219
	v_cvt_pk_fp8_f32 v249, v179, v254 op_sel:[0,0,1]
	ds_read_b128 v[90:93], v185 offset:32768
	ds_read_b128 v[94:97], v186 offset:32768
	s_waitcnt lgkmcnt(4)
	v_mfma_scale_f32_32x32x64_f8f6f4 v[114:129], v[82:89], v[138:145], v[114:129], v194, v193 op_sel_hi:[0,0,0]
	v_exp_f32_e32 v0, v66
	v_exp_f32_e32 v177, v67
	v_exp_f32_e32 v179, v68
	v_exp_f32_e32 v254, v69
	v_add_f32_e32 v219, v0, v219
	v_add_f32_e32 v219, v177, v219
	v_cvt_pk_fp8_f32 v250, v0, v177
	v_add_f32_e32 v219, v179, v219
	v_add_f32_e32 v219, v254, v219
	v_cvt_pk_fp8_f32 v250, v179, v254 op_sel:[0,0,1]
	s_waitcnt lgkmcnt(2)
	v_mfma_scale_f32_32x32x64_f8f6f4 v[98:113], v[222:229], v[138:145], v[98:113], v194, v193 op_sel_hi:[0,0,0]
	ds_read_b128 v[222:225], v185 offset:34816
	ds_read_b128 v[226:229], v186 offset:34816
	v_exp_f32_e32 v0, v70
	v_exp_f32_e32 v177, v71
	v_exp_f32_e32 v179, v72
	v_exp_f32_e32 v254, v73
	v_add_f32_e32 v219, v0, v219
	v_add_f32_e32 v219, v177, v219
	v_cvt_pk_fp8_f32 v251, v0, v177
	v_add_f32_e32 v219, v179, v219
	v_add_f32_e32 v219, v254, v219
	v_cvt_pk_fp8_f32 v251, v179, v254 op_sel:[0,0,1]
	v_exp_f32_e32 v0, v74
	v_exp_f32_e32 v177, v75
	v_exp_f32_e32 v179, v76
	v_exp_f32_e32 v254, v77
	v_add_f32_e32 v219, v0, v219
	v_add_f32_e32 v219, v177, v219
	v_cvt_pk_fp8_f32 v252, v0, v177
	v_add_f32_e32 v219, v179, v219
	v_add_f32_e32 v219, v254, v219
	v_cvt_pk_fp8_f32 v252, v179, v254 op_sel:[0,0,1]
	s_waitcnt lgkmcnt(2)
	v_mfma_scale_f32_32x32x64_f8f6f4 v[114:129], v[90:97], v[130:137], v[114:129], v194, v193 op_sel_hi:[0,0,0]
	v_exp_f32_e32 v0, v78
	v_exp_f32_e32 v177, v79
	v_exp_f32_e32 v179, v80
	v_exp_f32_e32 v254, v81
	v_add_f32_e32 v219, v0, v219
	v_add_f32_e32 v219, v177, v219
	v_cvt_pk_fp8_f32 v253, v0, v177
	v_add_f32_e32 v219, v179, v219
	v_add_f32_e32 v219, v254, v219
	v_cvt_pk_fp8_f32 v253, v179, v254 op_sel:[0,0,1]
	ds_read_b128 v[90:93], v185 offset:43008
	ds_read_b128 v[94:97], v186 offset:43008
	ds_read_b128 v[82:85], v185 offset:45056
	ds_read_b128 v[86:89], v186 offset:45056
	ds_read_b128 v[74:77], v185 offset:47104
	ds_read_b128 v[78:81], v186 offset:47104
	ds_read_b128 v[66:69], v185 offset:49152
	ds_read_b128 v[70:73], v186 offset:49152
	s_waitcnt lgkmcnt(8)
	v_mfma_scale_f32_32x32x64_f8f6f4 v[98:113], v[222:229], v[130:137], v[98:113], v194, v193 op_sel_hi:[0,0,0]
	v_mov_b32_e32 v0, v219
	s_nop 1
	v_permlane32_swap_b32_e32 v219, v0
	v_add_f32_e32 v219, v219, v0
	v_fma_f32 v209, v209, v218, v219
	v_max_f32_e32 v177, v114, v115
	v_max3_f32 v177, v177, v116, v117
	v_max3_f32 v177, v177, v118, v119
	v_max3_f32 v177, v177, v120, v121
	v_max3_f32 v177, v177, v122, v123
	v_max3_f32 v177, v177, v124, v125
	v_max3_f32 v177, v177, v126, v127
	v_max3_f32 v177, v177, v128, v129
	s_waitcnt lgkmcnt(6)
	v_mfma_scale_f32_32x32x64_f8f6f4 v[50:65], v[246:253], v[90:97], v[50:65], v194, v194 op_sel_hi:[0,0,0]
	s_waitcnt vmcnt(0)
	ds_write_b128 v210, v[158:161] offset:8192
	ds_write_b128 v211, v[162:165] offset:24576
	s_waitcnt lgkmcnt(6)
	v_mfma_scale_f32_32x32x64_f8f6f4 v[34:49], v[246:253], v[82:89], v[34:49], v194, v194 op_sel_hi:[0,0,0]
	s_waitcnt lgkmcnt(0)
	s_barrier
	s_waitcnt lgkmcnt(2)
	v_mfma_scale_f32_32x32x64_f8f6f4 v[18:33], v[246:253], v[74:81], v[18:33], v194, v194 op_sel_hi:[0,0,0]
	s_waitcnt lgkmcnt(0)
	v_mfma_scale_f32_32x32x64_f8f6f4 v[2:17], v[246:253], v[66:73], v[2:17], v194, v194 op_sel_hi:[0,0,0]
	global_load_dwordx4 v[158:161], v176, s[18:19]
	global_load_dwordx4 v[162:165], v178, s[16:17]
	v_add_u32_e32 v176, 0x2000, v176
	v_add_u32_e32 v178, 0x20000, v178
	v_max_f32_e32 v0, v98, v99
	v_max3_f32 v0, v0, v100, v101
	v_max3_f32 v0, v0, v102, v103
	v_max3_f32 v0, v0, v104, v105
	v_max3_f32 v0, v0, v106, v107
	v_max3_f32 v0, v0, v108, v109
	v_max3_f32 v0, v0, v110, v111
	v_max3_f32 v0, v0, v112, v113
	v_max_f32_e32 v177, v177, v0
	v_mov_b32_e32 v0, v177
	v_mov_b32_e32 v221, 1.0
	s_nop 0
	v_permlane32_swap_b32_e32 v177, v0
	v_max_f32_e32 v177, v177, v0
	v_cmp_ge_f32_e32 vcc, s90, v177
	s_cmp_eq_u64 vcc, exec
	s_cbranch_scc0 .Lmla_s2_newmax
; __device__ __forceinline__ void finishSM9(f32x16& p0, f32x16& p1, float alpha, float& l_reg, v8i32& p8) {
; #pragma unroll
;   for (int r = 0; r < 16; ++r) { p0[r] = __builtin_amdgcn_exp2f(p0[r]); p1[r] = __builtin_amdgcn_exp2f(p1[r]); }
;   float ps = 0;
; #pragma unroll
;   for (int r = 0; r < 16; ++r) ps += p0[r];
; #pragma unroll
;   for (int r = 0; r < 16; ++r) ps += p1[r];
;   { auto rr = __builtin_amdgcn_permlane32_swap(__float_as_uint(ps), __float_as_uint(ps), false, false);
;     ps = __uint_as_float(rr[0]) + __uint_as_float(rr[1]); }
;   l_reg = l_reg * alpha + ps;
; #pragma unroll
;   for (int g = 0; g < 4; ++g) {
;     int w = __builtin_amdgcn_cvt_pk_fp8_f32(p0[4 * g], p0[4 * g + 1], 0, false); p8[g] = __builtin_amdgcn_cvt_pk_fp8_f32(p0[4 * g + 2], p0[4 * g + 3], w, true);
;     int u = __builtin_amdgcn_cvt_pk_fp8_f32(p1[4 * g], p1[4 * g + 1], 0, false); p8[4 + g] = __builtin_amdgcn_cvt_pk_fp8_f32(p1[4 * g + 2], p1[4 * g + 3], u, true); }
; }
; __device__ __forceinline__ void pv8(f32x16* o, const char* Vt, const v8i32 p8, int r32, int hi) {
;   const int sw = (r32 >> 2) & 3, a0 = r32 * 64 + (((hi * 2) ^ sw) << 4), a1 = r32 * 64 + (((hi * 2 + 1) ^ sw) << 4);
; #pragma unroll
;   for (int d0 = 0; d0 < 4; ++d0) {
;     const v8i32 vf = cat8(*reinterpret_cast<const v4i32*>(Vt + d0 * 2048 + a0), *reinterpret_cast<const v4i32*>(Vt + d0 * 2048 + a1));
;     o[d0] = __builtin_amdgcn_mfma_scale_f32_32x32x64_f8f6f4(p8, vf, o[d0], 0, 0, 0, 127, 0, 127); }
; }
; __device__ __forceinline__ void qkt9(f32x16& p0, f32x16& p1, const char* Kn, const char* Kr, const v8i32* qf, const float init, int r32, int hi) {
; #pragma unroll
;   for (int r = 0; r < 16; ++r) { p0[r] = init; p1[r] = init; }
; #pragma unroll
;   for (int s = 0; s < 2; ++s) { const int c0 = s * 4 + hi * 2;
;     const v8i32 a0 = cat8(*reinterpret_cast<const v4i32*>(Kn + KN8SW(r32, c0)), *reinterpret_cast<const v4i32*>(Kn + KN8SW(r32, c0 + 1)));
;     const v8i32 a1 = cat8(*reinterpret_cast<const v4i32*>(Kn + 4096 + KN8SW(r32, c0)), *reinterpret_cast<const v4i32*>(Kn + 4096 + KN8SW(r32, c0 + 1)));
;     p0 = __builtin_amdgcn_mfma_scale_f32_32x32x64_f8f6f4(a0, qf[s], p0, 0, 0, 0, 127, 0, 124);
;     p1 = __builtin_amdgcn_mfma_scale_f32_32x32x64_f8f6f4(a1, qf[s], p1, 0, 0, 0, 127, 0, 124); }
;   { const int c0 = hi * 2;
.Lmla_s2_cont:
	ds_read_b128 v[82:85], v215 offset:24576
	ds_read_b128 v[86:89], v216 offset:24576
	ds_read_b128 v[222:225], v215 offset:28672
	ds_read_b128 v[226:229], v216 offset:28672
	v_exp_f32_e32 v0, v114
	v_exp_f32_e32 v177, v115
	v_exp_f32_e32 v179, v116
	v_exp_f32_e32 v254, v117
	v_add_f32_e32 v219, v0, v177
	v_cvt_pk_fp8_f32 v246, v0, v177
	v_add_f32_e32 v219, v179, v219
	v_add_f32_e32 v219, v254, v219
	v_cvt_pk_fp8_f32 v246, v179, v254 op_sel:[0,0,1]
	s_waitcnt lgkmcnt(2)
	v_mfma_scale_f32_32x32x64_f8f6f4 v[82:97], v[82:89], v[146:153], v[230:245], v194, v193 op_sel_hi:[0,0,0]
	v_exp_f32_e32 v0, v118
	v_exp_f32_e32 v177, v119
	v_exp_f32_e32 v179, v120
	v_exp_f32_e32 v254, v121
	v_add_f32_e32 v219, v0, v219
	v_add_f32_e32 v219, v177, v219
	v_cvt_pk_fp8_f32 v247, v0, v177
	v_add_f32_e32 v219, v179, v219
	v_add_f32_e32 v219, v254, v219
	v_cvt_pk_fp8_f32 v247, v179, v254 op_sel:[0,0,1]
	ds_read_b128 v[114:117], v213 offset:24576
	ds_read_b128 v[118:121], v214 offset:24576
	s_waitcnt lgkmcnt(2)
	v_mfma_scale_f32_32x32x64_f8f6f4 v[66:81], v[222:229], v[146:153], v[230:245], v194, v193 op_sel_hi:[0,0,0]
	ds_read_b128 v[222:225], v213 offset:28672
	ds_read_b128 v[226:229], v214 offset:28672
	v_exp_f32_e32 v0, v122
	v_exp_f32_e32 v177, v123
	v_exp_f32_e32 v179, v124
	v_exp_f32_e32 v254, v125
	v_add_f32_e32 v219, v0, v219
	v_add_f32_e32 v219, v177, v219
	v_cvt_pk_fp8_f32 v248, v0, v177
	v_add_f32_e32 v219, v179, v219
	v_add_f32_e32 v219, v254, v219
	v_cvt_pk_fp8_f32 v248, v179, v254 op_sel:[0,0,1]
	v_exp_f32_e32 v0, v126
	v_exp_f32_e32 v177, v127
	v_exp_f32_e32 v179, v128
	v_exp_f32_e32 v254, v129
	v_add_f32_e32 v219, v0, v219
	v_add_f32_e32 v219, v177, v219
	v_cvt_pk_fp8_f32 v249, v0, v177
	v_add_f32_e32 v219, v179, v219
	v_add_f32_e32 v219, v254, v219
	v_cvt_pk_fp8_f32 v249, v179, v254 op_sel:[0,0,1]
	ds_read_b128 v[122:125], v185 offset:36864
	ds_read_b128 v[126:129], v186 offset:36864
	s_waitcnt lgkmcnt(4)
	v_mfma_scale_f32_32x32x64_f8f6f4 v[82:97], v[114:121], v[138:145], v[82:97], v194, v193 op_sel_hi:[0,0,0]
	v_exp_f32_e32 v0, v98
	v_exp_f32_e32 v177, v99
	v_exp_f32_e32 v179, v100
	v_exp_f32_e32 v254, v101
	v_add_f32_e32 v219, v0, v219
	v_add_f32_e32 v219, v177, v219
	v_cvt_pk_fp8_f32 v250, v0, v177
	v_add_f32_e32 v219, v179, v219
	v_add_f32_e32 v219, v254, v219
	v_cvt_pk_fp8_f32 v250, v179, v254 op_sel:[0,0,1]
	s_waitcnt lgkmcnt(2)
	v_mfma_scale_f32_32x32x64_f8f6f4 v[66:81], v[222:229], v[138:145], v[66:81], v194, v193 op_sel_hi:[0,0,0]
	ds_read_b128 v[222:225], v185 offset:38912
	ds_read_b128 v[226:229], v186 offset:38912
	v_exp_f32_e32 v0, v102
	v_exp_f32_e32 v177, v103
	v_exp_f32_e32 v179, v104
	v_exp_f32_e32 v254, v105
	v_add_f32_e32 v219, v0, v219
	v_add_f32_e32 v219, v177, v219
	v_cvt_pk_fp8_f32 v251, v0, v177
	v_add_f32_e32 v219, v179, v219
	v_add_f32_e32 v219, v254, v219
	v_cvt_pk_fp8_f32 v251, v179, v254 op_sel:[0,0,1]
	v_exp_f32_e32 v0, v106
	v_exp_f32_e32 v177, v107
	v_exp_f32_e32 v179, v108
	v_exp_f32_e32 v254, v109
	v_add_f32_e32 v219, v0, v219
	v_add_f32_e32 v219, v177, v219
	v_cvt_pk_fp8_f32 v252, v0, v177
	v_add_f32_e32 v219, v179, v219
	v_add_f32_e32 v219, v254, v219
	v_cvt_pk_fp8_f32 v252, v179, v254 op_sel:[0,0,1]
	s_waitcnt lgkmcnt(2)
	v_mfma_scale_f32_32x32x64_f8f6f4 v[82:97], v[122:129], v[130:137], v[82:97], v194, v193 op_sel_hi:[0,0,0]
	v_exp_f32_e32 v0, v110
	v_exp_f32_e32 v177, v111
	v_exp_f32_e32 v179, v112
	v_exp_f32_e32 v254, v113
	v_add_f32_e32 v219, v0, v219
	v_add_f32_e32 v219, v177, v219
	v_cvt_pk_fp8_f32 v253, v0, v177
	v_add_f32_e32 v219, v179, v219
	v_add_f32_e32 v219, v254, v219
	v_cvt_pk_fp8_f32 v253, v179, v254 op_sel:[0,0,1]
	ds_read_b128 v[122:125], v185 offset:0
	ds_read_b128 v[126:129], v186 offset:0
	ds_read_b128 v[114:117], v185 offset:2048
	ds_read_b128 v[118:121], v186 offset:2048
	ds_read_b128 v[106:109], v185 offset:4096
	ds_read_b128 v[110:113], v186 offset:4096
	ds_read_b128 v[98:101], v185 offset:6144
	ds_read_b128 v[102:105], v186 offset:6144
	s_waitcnt lgkmcnt(8)
	v_mfma_scale_f32_32x32x64_f8f6f4 v[66:81], v[222:229], v[130:137], v[66:81], v194, v193 op_sel_hi:[0,0,0]
	v_mov_b32_e32 v0, v219
	s_nop 1
	v_permlane32_swap_b32_e32 v219, v0
	v_add_f32_e32 v219, v219, v0
	v_fma_f32 v209, v209, v221, v219
	v_max_f32_e32 v177, v82, v83
	v_max3_f32 v177, v177, v84, v85
	v_max3_f32 v177, v177, v86, v87
	v_max3_f32 v177, v177, v88, v89
	v_max3_f32 v177, v177, v90, v91
	v_max3_f32 v177, v177, v92, v93
	v_max3_f32 v177, v177, v94, v95
	v_max3_f32 v177, v177, v96, v97
	s_waitcnt lgkmcnt(6)
	v_mfma_scale_f32_32x32x64_f8f6f4 v[50:65], v[246:253], v[122:129], v[50:65], v194, v194 op_sel_hi:[0,0,0]
	s_waitcnt vmcnt(0)
	ds_write_b128 v210, v[158:161] offset:43008
	ds_write_b128 v211, v[162:165] offset:51200
	s_waitcnt lgkmcnt(6)
	v_mfma_scale_f32_32x32x64_f8f6f4 v[34:49], v[246:253], v[114:121], v[34:49], v194, v194 op_sel_hi:[0,0,0]
	s_waitcnt lgkmcnt(0)
	s_barrier
	s_waitcnt lgkmcnt(2)
	v_mfma_scale_f32_32x32x64_f8f6f4 v[18:33], v[246:253], v[106:113], v[18:33], v194, v194 op_sel_hi:[0,0,0]
	s_waitcnt lgkmcnt(0)
	v_mfma_scale_f32_32x32x64_f8f6f4 v[2:17], v[246:253], v[98:105], v[2:17], v194, v194 op_sel_hi:[0,0,0]
	global_load_dwordx4 v[158:161], v176, s[18:19]
	global_load_dwordx4 v[162:165], v178, s[16:17]
	v_add_u32_e32 v176, 0x2000, v176
	v_add_u32_e32 v178, 0x20000, v178
	v_max_f32_e32 v0, v66, v67
	v_max3_f32 v0, v0, v68, v69
	v_max3_f32 v0, v0, v70, v71
	v_max3_f32 v0, v0, v72, v73
	v_max3_f32 v0, v0, v74, v75
	v_max3_f32 v0, v0, v76, v77
	v_max3_f32 v0, v0, v78, v79
	v_max3_f32 v0, v0, v80, v81
	v_max_f32_e32 v177, v177, v0
	v_mov_b32_e32 v0, v177
	v_mov_b32_e32 v218, 1.0
	s_nop 0
	v_permlane32_swap_b32_e32 v177, v0
	v_max_f32_e32 v177, v177, v0
	v_cmp_ge_f32_e32 vcc, s90, v177
	s_cmp_eq_u64 vcc, exec
	s_cbranch_scc0 .Lmla_s3_newmax
; __device__ __forceinline__ void finishSM9(f32x16& p0, f32x16& p1, float alpha, float& l_reg, v8i32& p8) {
; #pragma unroll
;   for (int r = 0; r < 16; ++r) { p0[r] = __builtin_amdgcn_exp2f(p0[r]); p1[r] = __builtin_amdgcn_exp2f(p1[r]); }
;   float ps = 0;
; #pragma unroll
;   for (int r = 0; r < 16; ++r) ps += p0[r];
; #pragma unroll
;   for (int r = 0; r < 16; ++r) ps += p1[r];
;   { auto rr = __builtin_amdgcn_permlane32_swap(__float_as_uint(ps), __float_as_uint(ps), false, false);
;     ps = __uint_as_float(rr[0]) + __uint_as_float(rr[1]); }
;   l_reg = l_reg * alpha + ps;
; #pragma unroll
;   for (int g = 0; g < 4; ++g) {
;     int w = __builtin_amdgcn_cvt_pk_fp8_f32(p0[4 * g], p0[4 * g + 1], 0, false); p8[g] = __builtin_amdgcn_cvt_pk_fp8_f32(p0[4 * g + 2], p0[4 * g + 3], w, true);
;     int u = __builtin_amdgcn_cvt_pk_fp8_f32(p1[4 * g], p1[4 * g + 1], 0, false); p8[4 + g] = __builtin_amdgcn_cvt_pk_fp8_f32(p1[4 * g + 2], p1[4 * g + 3], u, true); }
; }
; __device__ __forceinline__ void pv8(f32x16* o, const char* Vt, const v8i32 p8, int r32, int hi) {
;   const int sw = (r32 >> 2) & 3, a0 = r32 * 64 + (((hi * 2) ^ sw) << 4), a1 = r32 * 64 + (((hi * 2 + 1) ^ sw) << 4);
; #pragma unroll
;   for (int d0 = 0; d0 < 4; ++d0) {
;     const v8i32 vf = cat8(*reinterpret_cast<const v4i32*>(Vt + d0 * 2048 + a0), *reinterpret_cast<const v4i32*>(Vt + d0 * 2048 + a1));
;     o[d0] = __builtin_amdgcn_mfma_scale_f32_32x32x64_f8f6f4(p8, vf, o[d0], 0, 0, 0, 127, 0, 127); }
; }
; __device__ __forceinline__ void qkt9(f32x16& p0, f32x16& p1, const char* Kn, const char* Kr, const v8i32* qf, const float init, int r32, int hi) {
; #pragma unroll
;   for (int r = 0; r < 16; ++r) { p0[r] = init; p1[r] = init; }
; #pragma unroll
;   for (int s = 0; s < 2; ++s) { const int c0 = s * 4 + hi * 2;
;     const v8i32 a0 = cat8(*reinterpret_cast<const v4i32*>(Kn + KN8SW(r32, c0)), *reinterpret_cast<const v4i32*>(Kn + KN8SW(r32, c0 + 1)));
;     const v8i32 a1 = cat8(*reinterpret_cast<const v4i32*>(Kn + 4096 + KN8SW(r32, c0)), *reinterpret_cast<const v4i32*>(Kn + 4096 + KN8SW(r32, c0 + 1)));
;     p0 = __builtin_amdgcn_mfma_scale_f32_32x32x64_f8f6f4(a0, qf[s], p0, 0, 0, 0, 127, 0, 124);
;     p1 = __builtin_amdgcn_mfma_scale_f32_32x32x64_f8f6f4(a1, qf[s], p1, 0, 0, 0, 127, 0, 124); }
;   { const int c0 = hi * 2;
.Lmla_s3_cont:
	ds_read_b128 v[114:117], v215 offset:51200
	ds_read_b128 v[118:121], v216 offset:51200
	ds_read_b128 v[222:225], v215 offset:55296
	ds_read_b128 v[226:229], v216 offset:55296
	v_exp_f32_e32 v0, v82
	v_exp_f32_e32 v177, v83
	v_exp_f32_e32 v179, v84
	v_exp_f32_e32 v254, v85
	v_add_f32_e32 v219, v0, v177
	v_cvt_pk_fp8_f32 v246, v0, v177
	v_add_f32_e32 v219, v179, v219
	v_add_f32_e32 v219, v254, v219
	v_cvt_pk_fp8_f32 v246, v179, v254 op_sel:[0,0,1]
	s_waitcnt lgkmcnt(2)
	v_mfma_scale_f32_32x32x64_f8f6f4 v[114:129], v[114:121], v[146:153], v[230:245], v194, v193 op_sel_hi:[0,0,0]
	v_exp_f32_e32 v0, v86
	v_exp_f32_e32 v177, v87
	v_exp_f32_e32 v179, v88
	v_exp_f32_e32 v254, v89
	v_add_f32_e32 v219, v0, v219
	v_add_f32_e32 v219, v177, v219
	v_cvt_pk_fp8_f32 v247, v0, v177
	v_add_f32_e32 v219, v179, v219
	v_add_f32_e32 v219, v254, v219
	v_cvt_pk_fp8_f32 v247, v179, v254 op_sel:[0,0,1]
	ds_read_b128 v[82:85], v213 offset:51200
	ds_read_b128 v[86:89], v214 offset:51200
	s_waitcnt lgkmcnt(2)
	v_mfma_scale_f32_32x32x64_f8f6f4 v[98:113], v[222:229], v[146:153], v[230:245], v194, v193 op_sel_hi:[0,0,0]
	ds_read_b128 v[222:225], v213 offset:55296
	ds_read_b128 v[226:229], v214 offset:55296
	v_exp_f32_e32 v0, v90
	v_exp_f32_e32 v177, v91
	v_exp_f32_e32 v179, v92
	v_exp_f32_e32 v254, v93
	v_add_f32_e32 v219, v0, v219
	v_add_f32_e32 v219, v177, v219
	v_cvt_pk_fp8_f32 v248, v0, v177
	v_add_f32_e32 v219, v179, v219
	v_add_f32_e32 v219, v254, v219
	v_cvt_pk_fp8_f32 v248, v179, v254 op_sel:[0,0,1]
	v_exp_f32_e32 v0, v94
	v_exp_f32_e32 v177, v95
	v_exp_f32_e32 v179, v96
	v_exp_f32_e32 v254, v97
	v_add_f32_e32 v219, v0, v219
	v_add_f32_e32 v219, v177, v219
	v_cvt_pk_fp8_f32 v249, v0, v177
	v_add_f32_e32 v219, v179, v219
	v_add_f32_e32 v219, v254, v219
	v_cvt_pk_fp8_f32 v249, v179, v254 op_sel:[0,0,1]
	ds_read_b128 v[90:93], v185 offset:59392
	ds_read_b128 v[94:97], v186 offset:59392
	s_waitcnt lgkmcnt(4)
	v_mfma_scale_f32_32x32x64_f8f6f4 v[114:129], v[82:89], v[138:145], v[114:129], v194, v193 op_sel_hi:[0,0,0]
	v_exp_f32_e32 v0, v66
	v_exp_f32_e32 v177, v67
	v_exp_f32_e32 v179, v68
	v_exp_f32_e32 v254, v69
	v_add_f32_e32 v219, v0, v219
	v_add_f32_e32 v219, v177, v219
	v_cvt_pk_fp8_f32 v250, v0, v177
	v_add_f32_e32 v219, v179, v219
	v_add_f32_e32 v219, v254, v219
	v_cvt_pk_fp8_f32 v250, v179, v254 op_sel:[0,0,1]
	s_waitcnt lgkmcnt(2)
	v_mfma_scale_f32_32x32x64_f8f6f4 v[98:113], v[222:229], v[138:145], v[98:113], v194, v193 op_sel_hi:[0,0,0]
	ds_read_b128 v[222:225], v185 offset:61440
	ds_read_b128 v[226:229], v186 offset:61440
	v_exp_f32_e32 v0, v70
	v_exp_f32_e32 v177, v71
	v_exp_f32_e32 v179, v72
	v_exp_f32_e32 v254, v73
	v_add_f32_e32 v219, v0, v219
	v_add_f32_e32 v219, v177, v219
	v_cvt_pk_fp8_f32 v251, v0, v177
	v_add_f32_e32 v219, v179, v219
	v_add_f32_e32 v219, v254, v219
	v_cvt_pk_fp8_f32 v251, v179, v254 op_sel:[0,0,1]
	v_exp_f32_e32 v0, v74
	v_exp_f32_e32 v177, v75
	v_exp_f32_e32 v179, v76
	v_exp_f32_e32 v254, v77
	v_add_f32_e32 v219, v0, v219
	v_add_f32_e32 v219, v177, v219
	v_cvt_pk_fp8_f32 v252, v0, v177
	v_add_f32_e32 v219, v179, v219
	v_add_f32_e32 v219, v254, v219
	v_cvt_pk_fp8_f32 v252, v179, v254 op_sel:[0,0,1]
	s_waitcnt lgkmcnt(2)
	v_mfma_scale_f32_32x32x64_f8f6f4 v[114:129], v[90:97], v[130:137], v[114:129], v194, v193 op_sel_hi:[0,0,0]
	v_exp_f32_e32 v0, v78
	v_exp_f32_e32 v177, v79
	v_exp_f32_e32 v179, v80
	v_exp_f32_e32 v254, v81
	v_add_f32_e32 v219, v0, v219
	v_add_f32_e32 v219, v177, v219
	v_cvt_pk_fp8_f32 v253, v0, v177
	v_add_f32_e32 v219, v179, v219
	v_add_f32_e32 v219, v254, v219
	v_cvt_pk_fp8_f32 v253, v179, v254 op_sel:[0,0,1]
	ds_read_b128 v[90:93], v185 offset:8192
	ds_read_b128 v[94:97], v186 offset:8192
	ds_read_b128 v[82:85], v185 offset:10240
	ds_read_b128 v[86:89], v186 offset:10240
	ds_read_b128 v[74:77], v185 offset:12288
	ds_read_b128 v[78:81], v186 offset:12288
	ds_read_b128 v[66:69], v185 offset:14336
	ds_read_b128 v[70:73], v186 offset:14336
	s_waitcnt lgkmcnt(8)
	v_mfma_scale_f32_32x32x64_f8f6f4 v[98:113], v[222:229], v[130:137], v[98:113], v194, v193 op_sel_hi:[0,0,0]
	v_mov_b32_e32 v0, v219
	s_nop 1
	v_permlane32_swap_b32_e32 v219, v0
	v_add_f32_e32 v219, v219, v0
	v_fma_f32 v209, v209, v218, v219
	v_max_f32_e32 v177, v114, v115
	v_max3_f32 v177, v177, v116, v117
	v_max3_f32 v177, v177, v118, v119
	v_max3_f32 v177, v177, v120, v121
	v_max3_f32 v177, v177, v122, v123
	v_max3_f32 v177, v177, v124, v125
	v_max3_f32 v177, v177, v126, v127
	v_max3_f32 v177, v177, v128, v129
	s_waitcnt lgkmcnt(6)
	v_mfma_scale_f32_32x32x64_f8f6f4 v[50:65], v[246:253], v[90:97], v[50:65], v194, v194 op_sel_hi:[0,0,0]
	s_waitcnt vmcnt(0)
	ds_write_b128 v210, v[158:161]
	ds_write_b128 v211, v[162:165] offset:16384
	s_waitcnt lgkmcnt(6)
	v_mfma_scale_f32_32x32x64_f8f6f4 v[34:49], v[246:253], v[82:89], v[34:49], v194, v194 op_sel_hi:[0,0,0]
	s_waitcnt lgkmcnt(0)
	s_barrier
	s_waitcnt lgkmcnt(2)
	v_mfma_scale_f32_32x32x64_f8f6f4 v[18:33], v[246:253], v[74:81], v[18:33], v194, v194 op_sel_hi:[0,0,0]
	s_waitcnt lgkmcnt(0)
	v_mfma_scale_f32_32x32x64_f8f6f4 v[2:17], v[246:253], v[66:73], v[2:17], v194, v194 op_sel_hi:[0,0,0]
	global_load_dwordx4 v[158:161], v176, s[18:19]
	global_load_dwordx4 v[162:165], v178, s[16:17]
	v_add_u32_e32 v176, 0x2000, v176
	v_add_u32_e32 v178, 0x20000, v178
	v_max_f32_e32 v0, v98, v99
	v_max3_f32 v0, v0, v100, v101
	v_max3_f32 v0, v0, v102, v103
	v_max3_f32 v0, v0, v104, v105
	v_max3_f32 v0, v0, v106, v107
	v_max3_f32 v0, v0, v108, v109
	v_max3_f32 v0, v0, v110, v111
	v_max3_f32 v0, v0, v112, v113
	v_max_f32_e32 v177, v177, v0
	v_mov_b32_e32 v0, v177
	v_mov_b32_e32 v221, 1.0
	s_nop 0
	v_permlane32_swap_b32_e32 v177, v0
	v_max_f32_e32 v177, v177, v0
	v_cmp_ge_f32_e32 vcc, s90, v177
	s_cmp_eq_u64 vcc, exec
	s_cbranch_scc0 .Lmla_s4_newmax
; __device__ __forceinline__ void finishSM9(f32x16& p0, f32x16& p1, float alpha, float& l_reg, v8i32& p8) {
; #pragma unroll
;   for (int r = 0; r < 16; ++r) { p0[r] = __builtin_amdgcn_exp2f(p0[r]); p1[r] = __builtin_amdgcn_exp2f(p1[r]); }
;   float ps = 0;
; #pragma unroll
;   for (int r = 0; r < 16; ++r) ps += p0[r];
; #pragma unroll
;   for (int r = 0; r < 16; ++r) ps += p1[r];
;   { auto rr = __builtin_amdgcn_permlane32_swap(__float_as_uint(ps), __float_as_uint(ps), false, false);
;     ps = __uint_as_float(rr[0]) + __uint_as_float(rr[1]); }
;   l_reg = l_reg * alpha + ps;
; #pragma unroll
;   for (int g = 0; g < 4; ++g) {
;     int w = __builtin_amdgcn_cvt_pk_fp8_f32(p0[4 * g], p0[4 * g + 1], 0, false); p8[g] = __builtin_amdgcn_cvt_pk_fp8_f32(p0[4 * g + 2], p0[4 * g + 3], w, true);
;     int u = __builtin_amdgcn_cvt_pk_fp8_f32(p1[4 * g], p1[4 * g + 1], 0, false); p8[4 + g] = __builtin_amdgcn_cvt_pk_fp8_f32(p1[4 * g + 2], p1[4 * g + 3], u, true); }
; }
; __device__ __forceinline__ void pv8(f32x16* o, const char* Vt, const v8i32 p8, int r32, int hi) {
;   const int sw = (r32 >> 2) & 3, a0 = r32 * 64 + (((hi * 2) ^ sw) << 4), a1 = r32 * 64 + (((hi * 2 + 1) ^ sw) << 4);
; #pragma unroll
;   for (int d0 = 0; d0 < 4; ++d0) {
;     const v8i32 vf = cat8(*reinterpret_cast<const v4i32*>(Vt + d0 * 2048 + a0), *reinterpret_cast<const v4i32*>(Vt + d0 * 2048 + a1));
;     o[d0] = __builtin_amdgcn_mfma_scale_f32_32x32x64_f8f6f4(p8, vf, o[d0], 0, 0, 0, 127, 0, 127); }
; }
; __device__ __forceinline__ void qkt9(f32x16& p0, f32x16& p1, const char* Kn, const char* Kr, const v8i32* qf, const float init, int r32, int hi) {
; #pragma unroll
;   for (int r = 0; r < 16; ++r) { p0[r] = init; p1[r] = init; }
; #pragma unroll
;   for (int s = 0; s < 2; ++s) { const int c0 = s * 4 + hi * 2;
;     const v8i32 a0 = cat8(*reinterpret_cast<const v4i32*>(Kn + KN8SW(r32, c0)), *reinterpret_cast<const v4i32*>(Kn + KN8SW(r32, c0 + 1)));
;     const v8i32 a1 = cat8(*reinterpret_cast<const v4i32*>(Kn + 4096 + KN8SW(r32, c0)), *reinterpret_cast<const v4i32*>(Kn + 4096 + KN8SW(r32, c0 + 1)));
;     p0 = __builtin_amdgcn_mfma_scale_f32_32x32x64_f8f6f4(a0, qf[s], p0, 0, 0, 0, 127, 0, 124);
;     p1 = __builtin_amdgcn_mfma_scale_f32_32x32x64_f8f6f4(a1, qf[s], p1, 0, 0, 0, 127, 0, 124); }
;   { const int c0 = hi * 2;
.Lmla_s4_cont:
	ds_read_b128 v[82:85], v215 offset:16384
	ds_read_b128 v[86:89], v216 offset:16384
	ds_read_b128 v[222:225], v215 offset:20480
	ds_read_b128 v[226:229], v216 offset:20480
	v_exp_f32_e32 v0, v114
	v_exp_f32_e32 v177, v115
	v_exp_f32_e32 v179, v116
	v_exp_f32_e32 v254, v117
	v_add_f32_e32 v219, v0, v177
	v_cvt_pk_fp8_f32 v246, v0, v177
	v_add_f32_e32 v219, v179, v219
	v_add_f32_e32 v219, v254, v219
	v_cvt_pk_fp8_f32 v246, v179, v254 op_sel:[0,0,1]
	s_waitcnt lgkmcnt(2)
	v_mfma_scale_f32_32x32x64_f8f6f4 v[82:97], v[82:89], v[146:153], v[230:245], v194, v193 op_sel_hi:[0,0,0]
	v_exp_f32_e32 v0, v118
	v_exp_f32_e32 v177, v119
	v_exp_f32_e32 v179, v120
	v_exp_f32_e32 v254, v121
	v_add_f32_e32 v219, v0, v219
	v_add_f32_e32 v219, v177, v219
	v_cvt_pk_fp8_f32 v247, v0, v177
	v_add_f32_e32 v219, v179, v219
	v_add_f32_e32 v219, v254, v219
	v_cvt_pk_fp8_f32 v247, v179, v254 op_sel:[0,0,1]
	ds_read_b128 v[114:117], v213 offset:16384
	ds_read_b128 v[118:121], v214 offset:16384
	s_waitcnt lgkmcnt(2)
	v_mfma_scale_f32_32x32x64_f8f6f4 v[66:81], v[222:229], v[146:153], v[230:245], v194, v193 op_sel_hi:[0,0,0]
	ds_read_b128 v[222:225], v213 offset:20480
	ds_read_b128 v[226:229], v214 offset:20480
	v_exp_f32_e32 v0, v122
	v_exp_f32_e32 v177, v123
	v_exp_f32_e32 v179, v124
	v_exp_f32_e32 v254, v125
	v_add_f32_e32 v219, v0, v219
	v_add_f32_e32 v219, v177, v219
	v_cvt_pk_fp8_f32 v248, v0, v177
	v_add_f32_e32 v219, v179, v219
	v_add_f32_e32 v219, v254, v219
	v_cvt_pk_fp8_f32 v248, v179, v254 op_sel:[0,0,1]
	v_exp_f32_e32 v0, v126
	v_exp_f32_e32 v177, v127
	v_exp_f32_e32 v179, v128
	v_exp_f32_e32 v254, v129
	v_add_f32_e32 v219, v0, v219
	v_add_f32_e32 v219, v177, v219
	v_cvt_pk_fp8_f32 v249, v0, v177
	v_add_f32_e32 v219, v179, v219
	v_add_f32_e32 v219, v254, v219
	v_cvt_pk_fp8_f32 v249, v179, v254 op_sel:[0,0,1]
	ds_read_b128 v[122:125], v185 offset:32768
	ds_read_b128 v[126:129], v186 offset:32768
	s_waitcnt lgkmcnt(4)
	v_mfma_scale_f32_32x32x64_f8f6f4 v[82:97], v[114:121], v[138:145], v[82:97], v194, v193 op_sel_hi:[0,0,0]
	v_exp_f32_e32 v0, v98
	v_exp_f32_e32 v177, v99
	v_exp_f32_e32 v179, v100
	v_exp_f32_e32 v254, v101
	v_add_f32_e32 v219, v0, v219
	v_add_f32_e32 v219, v177, v219
	v_cvt_pk_fp8_f32 v250, v0, v177
	v_add_f32_e32 v219, v179, v219
	v_add_f32_e32 v219, v254, v219
	v_cvt_pk_fp8_f32 v250, v179, v254 op_sel:[0,0,1]
	s_waitcnt lgkmcnt(2)
	v_mfma_scale_f32_32x32x64_f8f6f4 v[66:81], v[222:229], v[138:145], v[66:81], v194, v193 op_sel_hi:[0,0,0]
	ds_read_b128 v[222:225], v185 offset:34816
	ds_read_b128 v[226:229], v186 offset:34816
	v_exp_f32_e32 v0, v102
	v_exp_f32_e32 v177, v103
	v_exp_f32_e32 v179, v104
	v_exp_f32_e32 v254, v105
	v_add_f32_e32 v219, v0, v219
	v_add_f32_e32 v219, v177, v219
	v_cvt_pk_fp8_f32 v251, v0, v177
	v_add_f32_e32 v219, v179, v219
	v_add_f32_e32 v219, v254, v219
	v_cvt_pk_fp8_f32 v251, v179, v254 op_sel:[0,0,1]
	v_exp_f32_e32 v0, v106
	v_exp_f32_e32 v177, v107
	v_exp_f32_e32 v179, v108
	v_exp_f32_e32 v254, v109
	v_add_f32_e32 v219, v0, v219
	v_add_f32_e32 v219, v177, v219
	v_cvt_pk_fp8_f32 v252, v0, v177
	v_add_f32_e32 v219, v179, v219
	v_add_f32_e32 v219, v254, v219
	v_cvt_pk_fp8_f32 v252, v179, v254 op_sel:[0,0,1]
	s_waitcnt lgkmcnt(2)
	v_mfma_scale_f32_32x32x64_f8f6f4 v[82:97], v[122:129], v[130:137], v[82:97], v194, v193 op_sel_hi:[0,0,0]
	v_exp_f32_e32 v0, v110
	v_exp_f32_e32 v177, v111
	v_exp_f32_e32 v179, v112
	v_exp_f32_e32 v254, v113
	v_add_f32_e32 v219, v0, v219
	v_add_f32_e32 v219, v177, v219
	v_cvt_pk_fp8_f32 v253, v0, v177
	v_add_f32_e32 v219, v179, v219
	v_add_f32_e32 v219, v254, v219
	v_cvt_pk_fp8_f32 v253, v179, v254 op_sel:[0,0,1]
	ds_read_b128 v[122:125], v185 offset:43008
	ds_read_b128 v[126:129], v186 offset:43008
	ds_read_b128 v[114:117], v185 offset:45056
	ds_read_b128 v[118:121], v186 offset:45056
	ds_read_b128 v[106:109], v185 offset:47104
	ds_read_b128 v[110:113], v186 offset:47104
	ds_read_b128 v[98:101], v185 offset:49152
	ds_read_b128 v[102:105], v186 offset:49152
	s_waitcnt lgkmcnt(8)
	v_mfma_scale_f32_32x32x64_f8f6f4 v[66:81], v[222:229], v[130:137], v[66:81], v194, v193 op_sel_hi:[0,0,0]
	v_mov_b32_e32 v0, v219
	s_nop 1
	v_permlane32_swap_b32_e32 v219, v0
	v_add_f32_e32 v219, v219, v0
	v_fma_f32 v209, v209, v221, v219
	v_max_f32_e32 v177, v82, v83
	v_max3_f32 v177, v177, v84, v85
	v_max3_f32 v177, v177, v86, v87
	v_max3_f32 v177, v177, v88, v89
	v_max3_f32 v177, v177, v90, v91
	v_max3_f32 v177, v177, v92, v93
	v_max3_f32 v177, v177, v94, v95
	v_max3_f32 v177, v177, v96, v97
	s_waitcnt lgkmcnt(6)
	v_mfma_scale_f32_32x32x64_f8f6f4 v[50:65], v[246:253], v[122:129], v[50:65], v194, v194 op_sel_hi:[0,0,0]
	s_waitcnt vmcnt(0)
	ds_write_b128 v210, v[158:161] offset:8192
	ds_write_b128 v211, v[162:165] offset:24576
	s_waitcnt lgkmcnt(6)
	v_mfma_scale_f32_32x32x64_f8f6f4 v[34:49], v[246:253], v[114:121], v[34:49], v194, v194 op_sel_hi:[0,0,0]
	s_waitcnt lgkmcnt(0)
	s_barrier
	s_waitcnt lgkmcnt(2)
	v_mfma_scale_f32_32x32x64_f8f6f4 v[18:33], v[246:253], v[106:113], v[18:33], v194, v194 op_sel_hi:[0,0,0]
	s_waitcnt lgkmcnt(0)
	v_mfma_scale_f32_32x32x64_f8f6f4 v[2:17], v[246:253], v[98:105], v[2:17], v194, v194 op_sel_hi:[0,0,0]
	global_load_dwordx4 v[158:161], v176, s[18:19]
	global_load_dwordx4 v[162:165], v178, s[16:17]
	v_add_u32_e32 v176, 0x2000, v176
	v_add_u32_e32 v178, 0x20000, v178
	v_max_f32_e32 v0, v66, v67
	v_max3_f32 v0, v0, v68, v69
	v_max3_f32 v0, v0, v70, v71
	v_max3_f32 v0, v0, v72, v73
	v_max3_f32 v0, v0, v74, v75
	v_max3_f32 v0, v0, v76, v77
	v_max3_f32 v0, v0, v78, v79
	v_max3_f32 v0, v0, v80, v81
	v_max_f32_e32 v177, v177, v0
	v_mov_b32_e32 v0, v177
	v_mov_b32_e32 v218, 1.0
	s_nop 0
	v_permlane32_swap_b32_e32 v177, v0
	v_max_f32_e32 v177, v177, v0
	v_cmp_ge_f32_e32 vcc, s90, v177
	s_cmp_eq_u64 vcc, exec
	s_cbranch_scc0 .Lmla_s5_newmax
; __device__ __forceinline__ void finishSM9(f32x16& p0, f32x16& p1, float alpha, float& l_reg, v8i32& p8) {
; #pragma unroll
;   for (int r = 0; r < 16; ++r) { p0[r] = __builtin_amdgcn_exp2f(p0[r]); p1[r] = __builtin_amdgcn_exp2f(p1[r]); }
;   float ps = 0;
; #pragma unroll
;   for (int r = 0; r < 16; ++r) ps += p0[r];
; #pragma unroll
;   for (int r = 0; r < 16; ++r) ps += p1[r];
;   { auto rr = __builtin_amdgcn_permlane32_swap(__float_as_uint(ps), __float_as_uint(ps), false, false);
;     ps = __uint_as_float(rr[0]) + __uint_as_float(rr[1]); }
;   l_reg = l_reg * alpha + ps;
; #pragma unroll
;   for (int g = 0; g < 4; ++g) {
;     int w = __builtin_amdgcn_cvt_pk_fp8_f32(p0[4 * g], p0[4 * g + 1], 0, false); p8[g] = __builtin_amdgcn_cvt_pk_fp8_f32(p0[4 * g + 2], p0[4 * g + 3], w, true);
;     int u = __builtin_amdgcn_cvt_pk_fp8_f32(p1[4 * g], p1[4 * g + 1], 0, false); p8[4 + g] = __builtin_amdgcn_cvt_pk_fp8_f32(p1[4 * g + 2], p1[4 * g + 3], u, true); }
; }
; __device__ __forceinline__ void pv8(f32x16* o, const char* Vt, const v8i32 p8, int r32, int hi) {
;   const int sw = (r32 >> 2) & 3, a0 = r32 * 64 + (((hi * 2) ^ sw) << 4), a1 = r32 * 64 + (((hi * 2 + 1) ^ sw) << 4);
; #pragma unroll
;   for (int d0 = 0; d0 < 4; ++d0) {
;     const v8i32 vf = cat8(*reinterpret_cast<const v4i32*>(Vt + d0 * 2048 + a0), *reinterpret_cast<const v4i32*>(Vt + d0 * 2048 + a1));
;     o[d0] = __builtin_amdgcn_mfma_scale_f32_32x32x64_f8f6f4(p8, vf, o[d0], 0, 0, 0, 127, 0, 127); }
; }
; __device__ __forceinline__ void qkt9(f32x16& p0, f32x16& p1, const char* Kn, const char* Kr, const v8i32* qf, const float init, int r32, int hi) {
; #pragma unroll
;   for (int r = 0; r < 16; ++r) { p0[r] = init; p1[r] = init; }
; #pragma unroll
;   for (int s = 0; s < 2; ++s) { const int c0 = s * 4 + hi * 2;
;     const v8i32 a0 = cat8(*reinterpret_cast<const v4i32*>(Kn + KN8SW(r32, c0)), *reinterpret_cast<const v4i32*>(Kn + KN8SW(r32, c0 + 1)));
;     const v8i32 a1 = cat8(*reinterpret_cast<const v4i32*>(Kn + 4096 + KN8SW(r32, c0)), *reinterpret_cast<const v4i32*>(Kn + 4096 + KN8SW(r32, c0 + 1)));
;     p0 = __builtin_amdgcn_mfma_scale_f32_32x32x64_f8f6f4(a0, qf[s], p0, 0, 0, 0, 127, 0, 124);
;     p1 = __builtin_amdgcn_mfma_scale_f32_32x32x64_f8f6f4(a1, qf[s], p1, 0, 0, 0, 127, 0, 124); }
;   { const int c0 = hi * 2;
.Lmla_s5_cont:
	s_add_i32 s30, s30, 1
	s_cmpk_lt_u32 s30, 42
	s_cbranch_scc1 .Lmla_stag_loop
	ds_read_b128 v[114:117], v215 offset:24576
	ds_read_b128 v[118:121], v216 offset:24576
	ds_read_b128 v[222:225], v215 offset:28672
	ds_read_b128 v[226:229], v216 offset:28672
	v_exp_f32_e32 v0, v82
	v_exp_f32_e32 v177, v83
	v_exp_f32_e32 v179, v84
	v_exp_f32_e32 v254, v85
	v_add_f32_e32 v219, v0, v177
	v_cvt_pk_fp8_f32 v246, v0, v177
	v_add_f32_e32 v219, v179, v219
	v_add_f32_e32 v219, v254, v219
	v_cvt_pk_fp8_f32 v246, v179, v254 op_sel:[0,0,1]
	s_waitcnt lgkmcnt(2)
	v_mfma_scale_f32_32x32x64_f8f6f4 v[114:129], v[114:121], v[146:153], v[230:245], v194, v193 op_sel_hi:[0,0,0]
	v_exp_f32_e32 v0, v86
	v_exp_f32_e32 v177, v87
	v_exp_f32_e32 v179, v88
	v_exp_f32_e32 v254, v89
	v_add_f32_e32 v219, v0, v219
	v_add_f32_e32 v219, v177, v219
	v_cvt_pk_fp8_f32 v247, v0, v177
	v_add_f32_e32 v219, v179, v219
	v_add_f32_e32 v219, v254, v219
	v_cvt_pk_fp8_f32 v247, v179, v254 op_sel:[0,0,1]
	ds_read_b128 v[82:85], v213 offset:24576
	ds_read_b128 v[86:89], v214 offset:24576
	s_waitcnt lgkmcnt(2)
	v_mfma_scale_f32_32x32x64_f8f6f4 v[98:113], v[222:229], v[146:153], v[230:245], v194, v193 op_sel_hi:[0,0,0]
	ds_read_b128 v[222:225], v213 offset:28672
	ds_read_b128 v[226:229], v214 offset:28672
	v_exp_f32_e32 v0, v90
	v_exp_f32_e32 v177, v91
	v_exp_f32_e32 v179, v92
	v_exp_f32_e32 v254, v93
	v_add_f32_e32 v219, v0, v219
	v_add_f32_e32 v219, v177, v219
	v_cvt_pk_fp8_f32 v248, v0, v177
	v_add_f32_e32 v219, v179, v219
	v_add_f32_e32 v219, v254, v219
	v_cvt_pk_fp8_f32 v248, v179, v254 op_sel:[0,0,1]
	v_exp_f32_e32 v0, v94
	v_exp_f32_e32 v177, v95
	v_exp_f32_e32 v179, v96
	v_exp_f32_e32 v254, v97
	v_add_f32_e32 v219, v0, v219
	v_add_f32_e32 v219, v177, v219
	v_cvt_pk_fp8_f32 v249, v0, v177
	v_add_f32_e32 v219, v179, v219
	v_add_f32_e32 v219, v254, v219
	v_cvt_pk_fp8_f32 v249, v179, v254 op_sel:[0,0,1]
	ds_read_b128 v[90:93], v185 offset:36864
	ds_read_b128 v[94:97], v186 offset:36864
	s_waitcnt lgkmcnt(4)
	v_mfma_scale_f32_32x32x64_f8f6f4 v[114:129], v[82:89], v[138:145], v[114:129], v194, v193 op_sel_hi:[0,0,0]
	v_exp_f32_e32 v0, v66
	v_exp_f32_e32 v177, v67
	v_exp_f32_e32 v179, v68
	v_exp_f32_e32 v254, v69
	v_add_f32_e32 v219, v0, v219
	v_add_f32_e32 v219, v177, v219
	v_cvt_pk_fp8_f32 v250, v0, v177
	v_add_f32_e32 v219, v179, v219
	v_add_f32_e32 v219, v254, v219
	v_cvt_pk_fp8_f32 v250, v179, v254 op_sel:[0,0,1]
	s_waitcnt lgkmcnt(2)
	v_mfma_scale_f32_32x32x64_f8f6f4 v[98:113], v[222:229], v[138:145], v[98:113], v194, v193 op_sel_hi:[0,0,0]
	ds_read_b128 v[222:225], v185 offset:38912
	ds_read_b128 v[226:229], v186 offset:38912
	v_exp_f32_e32 v0, v70
	v_exp_f32_e32 v177, v71
	v_exp_f32_e32 v179, v72
	v_exp_f32_e32 v254, v73
	v_add_f32_e32 v219, v0, v219
	v_add_f32_e32 v219, v177, v219
	v_cvt_pk_fp8_f32 v251, v0, v177
	v_add_f32_e32 v219, v179, v219
	v_add_f32_e32 v219, v254, v219
	v_cvt_pk_fp8_f32 v251, v179, v254 op_sel:[0,0,1]
	v_exp_f32_e32 v0, v74
	v_exp_f32_e32 v177, v75
	v_exp_f32_e32 v179, v76
	v_exp_f32_e32 v254, v77
	v_add_f32_e32 v219, v0, v219
	v_add_f32_e32 v219, v177, v219
	v_cvt_pk_fp8_f32 v252, v0, v177
	v_add_f32_e32 v219, v179, v219
	v_add_f32_e32 v219, v254, v219
	v_cvt_pk_fp8_f32 v252, v179, v254 op_sel:[0,0,1]
	s_waitcnt lgkmcnt(2)
	v_mfma_scale_f32_32x32x64_f8f6f4 v[114:129], v[90:97], v[130:137], v[114:129], v194, v193 op_sel_hi:[0,0,0]
	v_exp_f32_e32 v0, v78
	v_exp_f32_e32 v177, v79
	v_exp_f32_e32 v179, v80
	v_exp_f32_e32 v254, v81
	v_add_f32_e32 v219, v0, v219
	v_add_f32_e32 v219, v177, v219
	v_cvt_pk_fp8_f32 v253, v0, v177
	v_add_f32_e32 v219, v179, v219
	v_add_f32_e32 v219, v254, v219
	v_cvt_pk_fp8_f32 v253, v179, v254 op_sel:[0,0,1]
	ds_read_b128 v[90:93], v185 offset:0
	ds_read_b128 v[94:97], v186 offset:0
	ds_read_b128 v[82:85], v185 offset:2048
	ds_read_b128 v[86:89], v186 offset:2048
	ds_read_b128 v[74:77], v185 offset:4096
	ds_read_b128 v[78:81], v186 offset:4096
	ds_read_b128 v[66:69], v185 offset:6144
	ds_read_b128 v[70:73], v186 offset:6144
	s_waitcnt lgkmcnt(8)
	v_mfma_scale_f32_32x32x64_f8f6f4 v[98:113], v[222:229], v[130:137], v[98:113], v194, v193 op_sel_hi:[0,0,0]
	v_mov_b32_e32 v0, v219
	s_nop 1
	v_permlane32_swap_b32_e32 v219, v0
	v_add_f32_e32 v219, v219, v0
	v_fma_f32 v209, v209, v218, v219
	v_max_f32_e32 v177, v114, v115
	v_max3_f32 v177, v177, v116, v117
	v_max3_f32 v177, v177, v118, v119
	v_max3_f32 v177, v177, v120, v121
	v_max3_f32 v177, v177, v122, v123
	v_max3_f32 v177, v177, v124, v125
	v_max3_f32 v177, v177, v126, v127
	v_max3_f32 v177, v177, v128, v129
	s_waitcnt lgkmcnt(6)
	v_mfma_scale_f32_32x32x64_f8f6f4 v[50:65], v[246:253], v[90:97], v[50:65], v194, v194 op_sel_hi:[0,0,0]
	s_waitcnt vmcnt(0)
	ds_write_b128 v210, v[158:161] offset:43008
	ds_write_b128 v211, v[162:165] offset:51200
	s_waitcnt lgkmcnt(6)
	v_mfma_scale_f32_32x32x64_f8f6f4 v[34:49], v[246:253], v[82:89], v[34:49], v194, v194 op_sel_hi:[0,0,0]
	s_waitcnt lgkmcnt(0)
	s_barrier
	s_waitcnt lgkmcnt(2)
	v_mfma_scale_f32_32x32x64_f8f6f4 v[18:33], v[246:253], v[74:81], v[18:33], v194, v194 op_sel_hi:[0,0,0]
	s_waitcnt lgkmcnt(0)
	v_mfma_scale_f32_32x32x64_f8f6f4 v[2:17], v[246:253], v[66:73], v[2:17], v194, v194 op_sel_hi:[0,0,0]
	global_load_dwordx4 v[158:161], v176, s[18:19]
	global_load_dwordx4 v[162:165], v178, s[16:17]
	v_add_u32_e32 v176, 0x2000, v176
	v_add_u32_e32 v178, 0x20000, v178
	v_max_f32_e32 v0, v98, v99
	v_max3_f32 v0, v0, v100, v101
	v_max3_f32 v0, v0, v102, v103
	v_max3_f32 v0, v0, v104, v105
	v_max3_f32 v0, v0, v106, v107
	v_max3_f32 v0, v0, v108, v109
	v_max3_f32 v0, v0, v110, v111
	v_max3_f32 v0, v0, v112, v113
	v_max_f32_e32 v177, v177, v0
	v_mov_b32_e32 v0, v177
	v_mov_b32_e32 v221, 1.0
	s_nop 0
	v_permlane32_swap_b32_e32 v177, v0
	v_max_f32_e32 v177, v177, v0
	v_cmp_ge_f32_e32 vcc, s90, v177
	s_cmp_eq_u64 vcc, exec
	s_cbranch_scc0 .Lmla_q0_newmax
